# fused panel norms (P7,P13,P16) hand-written: 8 rows per wave, all loads in flight
# speedup vs baseline: 1.0319x; 1.0092x over previous
.LBB0_1259:
	s_or_b64 exec, exec, s[10:11]
	s_sext_i32_i8 s5, s26
	s_lshl_b32 s4, s4, 8
	s_lshl_b32 s10, s5, 6
	v_mov_b32_e32 v1, v170
	s_waitcnt lgkmcnt(0)
	s_barrier
	s_load_dwordx2 s[52:53], s[0:1], 0xe8
	s_add_i32 s66, s4, s10
	v_readfirstlane_b32 s65, v170
	v_and_b32_e32 v226, 63, v170
	v_mov_b32_e32 v228, 0x358637bd
	v_lshlrev_b32_e32 v227, 3, v226
	v_lshlrev_b32_e32 v226, 4, v226
	s_lshr_b32 s65, s65, 6
	s_add_i32 s66, s66, s65
	s_waitcnt lgkmcnt(0)
	s_sub_i32 s67, s66, 0x1000
	s_ashr_i32 s67, s67, 11
	s_add_i32 s67, s67, 1
	s_cmp_gt_i32 s66, 0xfff
	s_cselect_b32 s67, s67, 0
	s_add_i32 s67, s67, 0
	s_mul_i32 s67, s67, 6
	s_add_i32 s67, s67, 3
	s_lshl_b32 s67, s67, 12
	s_add_u32 s58, s52, 0x780000
	s_addc_u32 s59, s53, 0
	s_add_u32 s58, s58, s67
	s_addc_u32 s59, s59, 0
	s_add_u32 s60, s58, 0x1000
	s_addc_u32 s61, s59, 0
	global_load_dwordx4 v[178:181], v226, s[58:59]
	global_load_dwordx4 v[182:185], v226, s[58:59] offset:1024
	global_load_dwordx4 v[186:189], v226, s[58:59] offset:2048
	global_load_dwordx4 v[190:193], v226, s[58:59] offset:3072
	global_load_dwordx4 v[194:197], v226, s[60:61]
	global_load_dwordx4 v[198:201], v226, s[60:61] offset:1024
	global_load_dwordx4 v[202:205], v226, s[60:61] offset:2048
	global_load_dwordx4 v[206:209], v226, s[60:61] offset:3072
	s_lshl_b32 s67, s66, 11
	s_add_u32 s56, s52, 0x2ebc000
	s_addc_u32 s57, s53, 0
	s_add_u32 s56, s56, s67
	s_addc_u32 s57, s57, 0
	s_lshl_b32 s67, s66, 12
	s_add_u32 s54, s52, 0x46bc000
	s_addc_u32 s55, s53, 0
	s_add_u32 s54, s54, s67
	s_addc_u32 s55, s55, 0
	global_load_dwordx4 v[0:3], v226, s[54:55]
	global_load_dwordx4 v[4:7], v226, s[54:55] offset:1024
	global_load_dwordx4 v[8:11], v226, s[54:55] offset:2048
	global_load_dwordx4 v[12:15], v226, s[54:55] offset:3072
	s_add_u32 s54, s54, 0x8000
	s_addc_u32 s55, s55, 0
	global_load_dwordx4 v[16:19], v226, s[54:55]
	global_load_dwordx4 v[20:23], v226, s[54:55] offset:1024
	global_load_dwordx4 v[24:27], v226, s[54:55] offset:2048
	global_load_dwordx4 v[28:31], v226, s[54:55] offset:3072
	s_add_u32 s54, s54, 0x8000
	s_addc_u32 s55, s55, 0
	global_load_dwordx4 v[32:35], v226, s[54:55]
	global_load_dwordx4 v[36:39], v226, s[54:55] offset:1024
	global_load_dwordx4 v[40:43], v226, s[54:55] offset:2048
	global_load_dwordx4 v[44:47], v226, s[54:55] offset:3072
	s_add_u32 s54, s54, 0x8000
	s_addc_u32 s55, s55, 0
	global_load_dwordx4 v[48:51], v226, s[54:55]
	global_load_dwordx4 v[52:55], v226, s[54:55] offset:1024
	global_load_dwordx4 v[56:59], v226, s[54:55] offset:2048
	global_load_dwordx4 v[60:63], v226, s[54:55] offset:3072
	s_add_u32 s54, s54, 0x8000
	s_addc_u32 s55, s55, 0
	global_load_dwordx4 v[64:67], v226, s[54:55]
	global_load_dwordx4 v[68:71], v226, s[54:55] offset:1024
	global_load_dwordx4 v[72:75], v226, s[54:55] offset:2048
	global_load_dwordx4 v[76:79], v226, s[54:55] offset:3072
	s_add_u32 s54, s54, 0x8000
	s_addc_u32 s55, s55, 0
	global_load_dwordx4 v[80:83], v226, s[54:55]
	global_load_dwordx4 v[84:87], v226, s[54:55] offset:1024
	global_load_dwordx4 v[88:91], v226, s[54:55] offset:2048
	global_load_dwordx4 v[92:95], v226, s[54:55] offset:3072
	s_add_u32 s54, s54, 0x8000
	s_addc_u32 s55, s55, 0
	global_load_dwordx4 v[134:137], v226, s[54:55]
	global_load_dwordx4 v[138:141], v226, s[54:55] offset:1024
	global_load_dwordx4 v[142:145], v226, s[54:55] offset:2048
	global_load_dwordx4 v[146:149], v226, s[54:55] offset:3072
	s_add_u32 s54, s54, 0x8000
	s_addc_u32 s55, s55, 0
	global_load_dwordx4 v[150:153], v226, s[54:55]
	global_load_dwordx4 v[154:157], v226, s[54:55] offset:1024
	global_load_dwordx4 v[158:161], v226, s[54:55] offset:2048
	global_load_dwordx4 v[162:165], v226, s[54:55] offset:3072
	s_waitcnt vmcnt(28)
	v_mul_f32_e32 v210, v0, v0
	v_fmac_f32_e32 v210, v1, v1
	v_fmac_f32_e32 v210, v2, v2
	v_fmac_f32_e32 v210, v3, v3
	v_fmac_f32_e32 v210, v4, v4
	v_fmac_f32_e32 v210, v5, v5
	v_fmac_f32_e32 v210, v6, v6
	v_fmac_f32_e32 v210, v7, v7
	v_fmac_f32_e32 v210, v8, v8
	v_fmac_f32_e32 v210, v9, v9
	v_fmac_f32_e32 v210, v10, v10
	v_fmac_f32_e32 v210, v11, v11
	v_fmac_f32_e32 v210, v12, v12
	v_fmac_f32_e32 v210, v13, v13
	v_fmac_f32_e32 v210, v14, v14
	v_fmac_f32_e32 v210, v15, v15
	s_waitcnt vmcnt(24)
	v_mul_f32_e32 v212, v16, v16
	v_fmac_f32_e32 v212, v17, v17
	v_fmac_f32_e32 v212, v18, v18
	v_fmac_f32_e32 v212, v19, v19
	v_fmac_f32_e32 v212, v20, v20
	v_fmac_f32_e32 v212, v21, v21
	v_fmac_f32_e32 v212, v22, v22
	v_fmac_f32_e32 v212, v23, v23
	v_fmac_f32_e32 v212, v24, v24
	v_fmac_f32_e32 v212, v25, v25
	v_fmac_f32_e32 v212, v26, v26
	v_fmac_f32_e32 v212, v27, v27
	v_fmac_f32_e32 v212, v28, v28
	v_fmac_f32_e32 v212, v29, v29
	v_fmac_f32_e32 v212, v30, v30
	v_fmac_f32_e32 v212, v31, v31
	s_waitcnt vmcnt(20)
	v_mul_f32_e32 v214, v32, v32
	v_fmac_f32_e32 v214, v33, v33
	v_fmac_f32_e32 v214, v34, v34
	v_fmac_f32_e32 v214, v35, v35
	v_fmac_f32_e32 v214, v36, v36
	v_fmac_f32_e32 v214, v37, v37
	v_fmac_f32_e32 v214, v38, v38
	v_fmac_f32_e32 v214, v39, v39
	v_fmac_f32_e32 v214, v40, v40
	v_fmac_f32_e32 v214, v41, v41
	v_fmac_f32_e32 v214, v42, v42
	v_fmac_f32_e32 v214, v43, v43
	v_fmac_f32_e32 v214, v44, v44
	v_fmac_f32_e32 v214, v45, v45
	v_fmac_f32_e32 v214, v46, v46
	v_fmac_f32_e32 v214, v47, v47
	s_waitcnt vmcnt(16)
	v_mul_f32_e32 v216, v48, v48
	v_fmac_f32_e32 v216, v49, v49
	v_fmac_f32_e32 v216, v50, v50
	v_fmac_f32_e32 v216, v51, v51
	v_fmac_f32_e32 v216, v52, v52
	v_fmac_f32_e32 v216, v53, v53
	v_fmac_f32_e32 v216, v54, v54
	v_fmac_f32_e32 v216, v55, v55
	v_fmac_f32_e32 v216, v56, v56
	v_fmac_f32_e32 v216, v57, v57
	v_fmac_f32_e32 v216, v58, v58
	v_fmac_f32_e32 v216, v59, v59
	v_fmac_f32_e32 v216, v60, v60
	v_fmac_f32_e32 v216, v61, v61
	v_fmac_f32_e32 v216, v62, v62
	v_fmac_f32_e32 v216, v63, v63
	s_waitcnt vmcnt(12)
	v_mul_f32_e32 v218, v64, v64
	v_fmac_f32_e32 v218, v65, v65
	v_fmac_f32_e32 v218, v66, v66
	v_fmac_f32_e32 v218, v67, v67
	v_fmac_f32_e32 v218, v68, v68
	v_fmac_f32_e32 v218, v69, v69
	v_fmac_f32_e32 v218, v70, v70
	v_fmac_f32_e32 v218, v71, v71
	v_fmac_f32_e32 v218, v72, v72
	v_fmac_f32_e32 v218, v73, v73
	v_fmac_f32_e32 v218, v74, v74
	v_fmac_f32_e32 v218, v75, v75
	v_fmac_f32_e32 v218, v76, v76
	v_fmac_f32_e32 v218, v77, v77
	v_fmac_f32_e32 v218, v78, v78
	v_fmac_f32_e32 v218, v79, v79
	s_waitcnt vmcnt(8)
	v_mul_f32_e32 v220, v80, v80
	v_fmac_f32_e32 v220, v81, v81
	v_fmac_f32_e32 v220, v82, v82
	v_fmac_f32_e32 v220, v83, v83
	v_fmac_f32_e32 v220, v84, v84
	v_fmac_f32_e32 v220, v85, v85
	v_fmac_f32_e32 v220, v86, v86
	v_fmac_f32_e32 v220, v87, v87
	v_fmac_f32_e32 v220, v88, v88
	v_fmac_f32_e32 v220, v89, v89
	v_fmac_f32_e32 v220, v90, v90
	v_fmac_f32_e32 v220, v91, v91
	v_fmac_f32_e32 v220, v92, v92
	v_fmac_f32_e32 v220, v93, v93
	v_fmac_f32_e32 v220, v94, v94
	v_fmac_f32_e32 v220, v95, v95
	s_waitcnt vmcnt(4)
	v_mul_f32_e32 v222, v134, v134
	v_fmac_f32_e32 v222, v135, v135
	v_fmac_f32_e32 v222, v136, v136
	v_fmac_f32_e32 v222, v137, v137
	v_fmac_f32_e32 v222, v138, v138
	v_fmac_f32_e32 v222, v139, v139
	v_fmac_f32_e32 v222, v140, v140
	v_fmac_f32_e32 v222, v141, v141
	v_fmac_f32_e32 v222, v142, v142
	v_fmac_f32_e32 v222, v143, v143
	v_fmac_f32_e32 v222, v144, v144
	v_fmac_f32_e32 v222, v145, v145
	v_fmac_f32_e32 v222, v146, v146
	v_fmac_f32_e32 v222, v147, v147
	v_fmac_f32_e32 v222, v148, v148
	v_fmac_f32_e32 v222, v149, v149
	s_waitcnt vmcnt(0)
	v_mul_f32_e32 v224, v150, v150
	v_fmac_f32_e32 v224, v151, v151
	v_fmac_f32_e32 v224, v152, v152
	v_fmac_f32_e32 v224, v153, v153
	v_fmac_f32_e32 v224, v154, v154
	v_fmac_f32_e32 v224, v155, v155
	v_fmac_f32_e32 v224, v156, v156
	v_fmac_f32_e32 v224, v157, v157
	v_fmac_f32_e32 v224, v158, v158
	v_fmac_f32_e32 v224, v159, v159
	v_fmac_f32_e32 v224, v160, v160
	v_fmac_f32_e32 v224, v161, v161
	v_fmac_f32_e32 v224, v162, v162
	v_fmac_f32_e32 v224, v163, v163
	v_fmac_f32_e32 v224, v164, v164
	v_fmac_f32_e32 v224, v165, v165
	ds_bpermute_b32 v211, v171, v210
	ds_bpermute_b32 v213, v171, v212
	ds_bpermute_b32 v215, v171, v214
	ds_bpermute_b32 v217, v171, v216
	ds_bpermute_b32 v219, v171, v218
	ds_bpermute_b32 v221, v171, v220
	ds_bpermute_b32 v223, v171, v222
	ds_bpermute_b32 v225, v171, v224
	s_waitcnt lgkmcnt(7)
	v_add_f32_e32 v210, v210, v211
	s_waitcnt lgkmcnt(6)
	v_add_f32_e32 v212, v212, v213
	s_waitcnt lgkmcnt(5)
	v_add_f32_e32 v214, v214, v215
	s_waitcnt lgkmcnt(4)
	v_add_f32_e32 v216, v216, v217
	s_waitcnt lgkmcnt(3)
	v_add_f32_e32 v218, v218, v219
	s_waitcnt lgkmcnt(2)
	v_add_f32_e32 v220, v220, v221
	s_waitcnt lgkmcnt(1)
	v_add_f32_e32 v222, v222, v223
	s_waitcnt lgkmcnt(0)
	v_add_f32_e32 v224, v224, v225
	ds_bpermute_b32 v211, v172, v210
	ds_bpermute_b32 v213, v172, v212
	ds_bpermute_b32 v215, v172, v214
	ds_bpermute_b32 v217, v172, v216
	ds_bpermute_b32 v219, v172, v218
	ds_bpermute_b32 v221, v172, v220
	ds_bpermute_b32 v223, v172, v222
	ds_bpermute_b32 v225, v172, v224
	s_waitcnt lgkmcnt(7)
	v_add_f32_e32 v210, v210, v211
	s_waitcnt lgkmcnt(6)
	v_add_f32_e32 v212, v212, v213
	s_waitcnt lgkmcnt(5)
	v_add_f32_e32 v214, v214, v215
	s_waitcnt lgkmcnt(4)
	v_add_f32_e32 v216, v216, v217
	s_waitcnt lgkmcnt(3)
	v_add_f32_e32 v218, v218, v219
	s_waitcnt lgkmcnt(2)
	v_add_f32_e32 v220, v220, v221
	s_waitcnt lgkmcnt(1)
	v_add_f32_e32 v222, v222, v223
	s_waitcnt lgkmcnt(0)
	v_add_f32_e32 v224, v224, v225
	ds_bpermute_b32 v211, v173, v210
	ds_bpermute_b32 v213, v173, v212
	ds_bpermute_b32 v215, v173, v214
	ds_bpermute_b32 v217, v173, v216
	ds_bpermute_b32 v219, v173, v218
	ds_bpermute_b32 v221, v173, v220
	ds_bpermute_b32 v223, v173, v222
	ds_bpermute_b32 v225, v173, v224
	s_waitcnt lgkmcnt(7)
	v_add_f32_e32 v210, v210, v211
	s_waitcnt lgkmcnt(6)
	v_add_f32_e32 v212, v212, v213
	s_waitcnt lgkmcnt(5)
	v_add_f32_e32 v214, v214, v215
	s_waitcnt lgkmcnt(4)
	v_add_f32_e32 v216, v216, v217
	s_waitcnt lgkmcnt(3)
	v_add_f32_e32 v218, v218, v219
	s_waitcnt lgkmcnt(2)
	v_add_f32_e32 v220, v220, v221
	s_waitcnt lgkmcnt(1)
	v_add_f32_e32 v222, v222, v223
	s_waitcnt lgkmcnt(0)
	v_add_f32_e32 v224, v224, v225
	ds_bpermute_b32 v211, v174, v210
	ds_bpermute_b32 v213, v174, v212
	ds_bpermute_b32 v215, v174, v214
	ds_bpermute_b32 v217, v174, v216
	ds_bpermute_b32 v219, v174, v218
	ds_bpermute_b32 v221, v174, v220
	ds_bpermute_b32 v223, v174, v222
	ds_bpermute_b32 v225, v174, v224
	s_waitcnt lgkmcnt(7)
	v_add_f32_e32 v210, v210, v211
	s_waitcnt lgkmcnt(6)
	v_add_f32_e32 v212, v212, v213
	s_waitcnt lgkmcnt(5)
	v_add_f32_e32 v214, v214, v215
	s_waitcnt lgkmcnt(4)
	v_add_f32_e32 v216, v216, v217
	s_waitcnt lgkmcnt(3)
	v_add_f32_e32 v218, v218, v219
	s_waitcnt lgkmcnt(2)
	v_add_f32_e32 v220, v220, v221
	s_waitcnt lgkmcnt(1)
	v_add_f32_e32 v222, v222, v223
	s_waitcnt lgkmcnt(0)
	v_add_f32_e32 v224, v224, v225
	ds_bpermute_b32 v211, v175, v210
	ds_bpermute_b32 v213, v175, v212
	ds_bpermute_b32 v215, v175, v214
	ds_bpermute_b32 v217, v175, v216
	ds_bpermute_b32 v219, v175, v218
	ds_bpermute_b32 v221, v175, v220
	ds_bpermute_b32 v223, v175, v222
	ds_bpermute_b32 v225, v175, v224
	s_waitcnt lgkmcnt(7)
	v_add_f32_e32 v210, v210, v211
	s_waitcnt lgkmcnt(6)
	v_add_f32_e32 v212, v212, v213
	s_waitcnt lgkmcnt(5)
	v_add_f32_e32 v214, v214, v215
	s_waitcnt lgkmcnt(4)
	v_add_f32_e32 v216, v216, v217
	s_waitcnt lgkmcnt(3)
	v_add_f32_e32 v218, v218, v219
	s_waitcnt lgkmcnt(2)
	v_add_f32_e32 v220, v220, v221
	s_waitcnt lgkmcnt(1)
	v_add_f32_e32 v222, v222, v223
	s_waitcnt lgkmcnt(0)
	v_add_f32_e32 v224, v224, v225
	ds_bpermute_b32 v211, v176, v210
	ds_bpermute_b32 v213, v176, v212
	ds_bpermute_b32 v215, v176, v214
	ds_bpermute_b32 v217, v176, v216
	ds_bpermute_b32 v219, v176, v218
	ds_bpermute_b32 v221, v176, v220
	ds_bpermute_b32 v223, v176, v222
	ds_bpermute_b32 v225, v176, v224
	s_waitcnt lgkmcnt(7)
	v_add_f32_e32 v210, v210, v211
	s_waitcnt lgkmcnt(6)
	v_add_f32_e32 v212, v212, v213
	s_waitcnt lgkmcnt(5)
	v_add_f32_e32 v214, v214, v215
	s_waitcnt lgkmcnt(4)
	v_add_f32_e32 v216, v216, v217
	s_waitcnt lgkmcnt(3)
	v_add_f32_e32 v218, v218, v219
	s_waitcnt lgkmcnt(2)
	v_add_f32_e32 v220, v220, v221
	s_waitcnt lgkmcnt(1)
	v_add_f32_e32 v222, v222, v223
	s_waitcnt lgkmcnt(0)
	v_add_f32_e32 v224, v224, v225
	v_fmamk_f32 v210, v210, 0x3a800000, v228
	v_fmamk_f32 v212, v212, 0x3a800000, v228
	v_fmamk_f32 v214, v214, 0x3a800000, v228
	v_fmamk_f32 v216, v216, 0x3a800000, v228
	v_fmamk_f32 v218, v218, 0x3a800000, v228
	v_fmamk_f32 v220, v220, 0x3a800000, v228
	v_fmamk_f32 v222, v222, 0x3a800000, v228
	v_fmamk_f32 v224, v224, 0x3a800000, v228
	v_rsq_f32_e32 v210, v210
	v_rsq_f32_e32 v212, v212
	v_rsq_f32_e32 v214, v214
	v_rsq_f32_e32 v216, v216
	v_rsq_f32_e32 v218, v218
	v_rsq_f32_e32 v220, v220
	v_rsq_f32_e32 v222, v222
	v_rsq_f32_e32 v224, v224
	v_pk_mul_f32 v[0:1], v[0:1], v[210:211] op_sel_hi:[1,0]
	v_pk_mul_f32 v[2:3], v[2:3], v[210:211] op_sel_hi:[1,0]
	v_pk_fma_f32 v[0:1], v[0:1], v[178:179], v[194:195]
	v_pk_fma_f32 v[2:3], v[2:3], v[180:181], v[196:197]
	v_cvt_pk_bf16_f32 v0, v0, v1
	v_cvt_pk_bf16_f32 v1, v2, v3
	global_store_dwordx2 v227, v[0:1], s[56:57]
	v_pk_mul_f32 v[4:5], v[4:5], v[210:211] op_sel_hi:[1,0]
	v_pk_mul_f32 v[6:7], v[6:7], v[210:211] op_sel_hi:[1,0]
	v_pk_fma_f32 v[4:5], v[4:5], v[182:183], v[198:199]
	v_pk_fma_f32 v[6:7], v[6:7], v[184:185], v[200:201]
	v_cvt_pk_bf16_f32 v4, v4, v5
	v_cvt_pk_bf16_f32 v5, v6, v7
	global_store_dwordx2 v227, v[4:5], s[56:57] offset:512
	v_pk_mul_f32 v[8:9], v[8:9], v[210:211] op_sel_hi:[1,0]
	v_pk_mul_f32 v[10:11], v[10:11], v[210:211] op_sel_hi:[1,0]
	v_pk_fma_f32 v[8:9], v[8:9], v[186:187], v[202:203]
	v_pk_fma_f32 v[10:11], v[10:11], v[188:189], v[204:205]
	v_cvt_pk_bf16_f32 v8, v8, v9
	v_cvt_pk_bf16_f32 v9, v10, v11
	global_store_dwordx2 v227, v[8:9], s[56:57] offset:1024
	v_pk_mul_f32 v[12:13], v[12:13], v[210:211] op_sel_hi:[1,0]
	v_pk_mul_f32 v[14:15], v[14:15], v[210:211] op_sel_hi:[1,0]
	v_pk_fma_f32 v[12:13], v[12:13], v[190:191], v[206:207]
	v_pk_fma_f32 v[14:15], v[14:15], v[192:193], v[208:209]
	v_cvt_pk_bf16_f32 v12, v12, v13
	v_cvt_pk_bf16_f32 v13, v14, v15
	global_store_dwordx2 v227, v[12:13], s[56:57] offset:1536
	s_add_u32 s56, s56, 0x4000
	s_addc_u32 s57, s57, 0
	v_pk_mul_f32 v[16:17], v[16:17], v[212:213] op_sel_hi:[1,0]
	v_pk_mul_f32 v[18:19], v[18:19], v[212:213] op_sel_hi:[1,0]
	v_pk_fma_f32 v[16:17], v[16:17], v[178:179], v[194:195]
	v_pk_fma_f32 v[18:19], v[18:19], v[180:181], v[196:197]
	v_cvt_pk_bf16_f32 v16, v16, v17
	v_cvt_pk_bf16_f32 v17, v18, v19
	global_store_dwordx2 v227, v[16:17], s[56:57]
	v_pk_mul_f32 v[20:21], v[20:21], v[212:213] op_sel_hi:[1,0]
	v_pk_mul_f32 v[22:23], v[22:23], v[212:213] op_sel_hi:[1,0]
	v_pk_fma_f32 v[20:21], v[20:21], v[182:183], v[198:199]
	v_pk_fma_f32 v[22:23], v[22:23], v[184:185], v[200:201]
	v_cvt_pk_bf16_f32 v20, v20, v21
	v_cvt_pk_bf16_f32 v21, v22, v23
	global_store_dwordx2 v227, v[20:21], s[56:57] offset:512
	v_pk_mul_f32 v[24:25], v[24:25], v[212:213] op_sel_hi:[1,0]
	v_pk_mul_f32 v[26:27], v[26:27], v[212:213] op_sel_hi:[1,0]
	v_pk_fma_f32 v[24:25], v[24:25], v[186:187], v[202:203]
	v_pk_fma_f32 v[26:27], v[26:27], v[188:189], v[204:205]
	v_cvt_pk_bf16_f32 v24, v24, v25
	v_cvt_pk_bf16_f32 v25, v26, v27
	global_store_dwordx2 v227, v[24:25], s[56:57] offset:1024
	v_pk_mul_f32 v[28:29], v[28:29], v[212:213] op_sel_hi:[1,0]
	v_pk_mul_f32 v[30:31], v[30:31], v[212:213] op_sel_hi:[1,0]
	v_pk_fma_f32 v[28:29], v[28:29], v[190:191], v[206:207]
	v_pk_fma_f32 v[30:31], v[30:31], v[192:193], v[208:209]
	v_cvt_pk_bf16_f32 v28, v28, v29
	v_cvt_pk_bf16_f32 v29, v30, v31
	global_store_dwordx2 v227, v[28:29], s[56:57] offset:1536
	s_add_u32 s56, s56, 0x4000
	s_addc_u32 s57, s57, 0
	v_pk_mul_f32 v[32:33], v[32:33], v[214:215] op_sel_hi:[1,0]
	v_pk_mul_f32 v[34:35], v[34:35], v[214:215] op_sel_hi:[1,0]
	v_pk_fma_f32 v[32:33], v[32:33], v[178:179], v[194:195]
	v_pk_fma_f32 v[34:35], v[34:35], v[180:181], v[196:197]
	v_cvt_pk_bf16_f32 v32, v32, v33
	v_cvt_pk_bf16_f32 v33, v34, v35
	global_store_dwordx2 v227, v[32:33], s[56:57]
	v_pk_mul_f32 v[36:37], v[36:37], v[214:215] op_sel_hi:[1,0]
	v_pk_mul_f32 v[38:39], v[38:39], v[214:215] op_sel_hi:[1,0]
	v_pk_fma_f32 v[36:37], v[36:37], v[182:183], v[198:199]
	v_pk_fma_f32 v[38:39], v[38:39], v[184:185], v[200:201]
	v_cvt_pk_bf16_f32 v36, v36, v37
	v_cvt_pk_bf16_f32 v37, v38, v39
	global_store_dwordx2 v227, v[36:37], s[56:57] offset:512
	v_pk_mul_f32 v[40:41], v[40:41], v[214:215] op_sel_hi:[1,0]
	v_pk_mul_f32 v[42:43], v[42:43], v[214:215] op_sel_hi:[1,0]
	v_pk_fma_f32 v[40:41], v[40:41], v[186:187], v[202:203]
	v_pk_fma_f32 v[42:43], v[42:43], v[188:189], v[204:205]
	v_cvt_pk_bf16_f32 v40, v40, v41
	v_cvt_pk_bf16_f32 v41, v42, v43
	global_store_dwordx2 v227, v[40:41], s[56:57] offset:1024
	v_pk_mul_f32 v[44:45], v[44:45], v[214:215] op_sel_hi:[1,0]
	v_pk_mul_f32 v[46:47], v[46:47], v[214:215] op_sel_hi:[1,0]
	v_pk_fma_f32 v[44:45], v[44:45], v[190:191], v[206:207]
	v_pk_fma_f32 v[46:47], v[46:47], v[192:193], v[208:209]
	v_cvt_pk_bf16_f32 v44, v44, v45
	v_cvt_pk_bf16_f32 v45, v46, v47
	global_store_dwordx2 v227, v[44:45], s[56:57] offset:1536
	s_add_u32 s56, s56, 0x4000
	s_addc_u32 s57, s57, 0
	v_pk_mul_f32 v[48:49], v[48:49], v[216:217] op_sel_hi:[1,0]
	v_pk_mul_f32 v[50:51], v[50:51], v[216:217] op_sel_hi:[1,0]
	v_pk_fma_f32 v[48:49], v[48:49], v[178:179], v[194:195]
	v_pk_fma_f32 v[50:51], v[50:51], v[180:181], v[196:197]
	v_cvt_pk_bf16_f32 v48, v48, v49
	v_cvt_pk_bf16_f32 v49, v50, v51
	global_store_dwordx2 v227, v[48:49], s[56:57]
	v_pk_mul_f32 v[52:53], v[52:53], v[216:217] op_sel_hi:[1,0]
	v_pk_mul_f32 v[54:55], v[54:55], v[216:217] op_sel_hi:[1,0]
	v_pk_fma_f32 v[52:53], v[52:53], v[182:183], v[198:199]
	v_pk_fma_f32 v[54:55], v[54:55], v[184:185], v[200:201]
	v_cvt_pk_bf16_f32 v52, v52, v53
	v_cvt_pk_bf16_f32 v53, v54, v55
	global_store_dwordx2 v227, v[52:53], s[56:57] offset:512
	v_pk_mul_f32 v[56:57], v[56:57], v[216:217] op_sel_hi:[1,0]
	v_pk_mul_f32 v[58:59], v[58:59], v[216:217] op_sel_hi:[1,0]
	v_pk_fma_f32 v[56:57], v[56:57], v[186:187], v[202:203]
	v_pk_fma_f32 v[58:59], v[58:59], v[188:189], v[204:205]
	v_cvt_pk_bf16_f32 v56, v56, v57
	v_cvt_pk_bf16_f32 v57, v58, v59
	global_store_dwordx2 v227, v[56:57], s[56:57] offset:1024
	v_pk_mul_f32 v[60:61], v[60:61], v[216:217] op_sel_hi:[1,0]
	v_pk_mul_f32 v[62:63], v[62:63], v[216:217] op_sel_hi:[1,0]
	v_pk_fma_f32 v[60:61], v[60:61], v[190:191], v[206:207]
	v_pk_fma_f32 v[62:63], v[62:63], v[192:193], v[208:209]
	v_cvt_pk_bf16_f32 v60, v60, v61
	v_cvt_pk_bf16_f32 v61, v62, v63
	global_store_dwordx2 v227, v[60:61], s[56:57] offset:1536
	s_add_u32 s56, s56, 0x4000
	s_addc_u32 s57, s57, 0
	v_pk_mul_f32 v[64:65], v[64:65], v[218:219] op_sel_hi:[1,0]
	v_pk_mul_f32 v[66:67], v[66:67], v[218:219] op_sel_hi:[1,0]
	v_pk_fma_f32 v[64:65], v[64:65], v[178:179], v[194:195]
	v_pk_fma_f32 v[66:67], v[66:67], v[180:181], v[196:197]
	v_cvt_pk_bf16_f32 v64, v64, v65
	v_cvt_pk_bf16_f32 v65, v66, v67
	global_store_dwordx2 v227, v[64:65], s[56:57]
	v_pk_mul_f32 v[68:69], v[68:69], v[218:219] op_sel_hi:[1,0]
	v_pk_mul_f32 v[70:71], v[70:71], v[218:219] op_sel_hi:[1,0]
	v_pk_fma_f32 v[68:69], v[68:69], v[182:183], v[198:199]
	v_pk_fma_f32 v[70:71], v[70:71], v[184:185], v[200:201]
	v_cvt_pk_bf16_f32 v68, v68, v69
	v_cvt_pk_bf16_f32 v69, v70, v71
	global_store_dwordx2 v227, v[68:69], s[56:57] offset:512
	v_pk_mul_f32 v[72:73], v[72:73], v[218:219] op_sel_hi:[1,0]
	v_pk_mul_f32 v[74:75], v[74:75], v[218:219] op_sel_hi:[1,0]
	v_pk_fma_f32 v[72:73], v[72:73], v[186:187], v[202:203]
	v_pk_fma_f32 v[74:75], v[74:75], v[188:189], v[204:205]
	v_cvt_pk_bf16_f32 v72, v72, v73
	v_cvt_pk_bf16_f32 v73, v74, v75
	global_store_dwordx2 v227, v[72:73], s[56:57] offset:1024
	v_pk_mul_f32 v[76:77], v[76:77], v[218:219] op_sel_hi:[1,0]
	v_pk_mul_f32 v[78:79], v[78:79], v[218:219] op_sel_hi:[1,0]
	v_pk_fma_f32 v[76:77], v[76:77], v[190:191], v[206:207]
	v_pk_fma_f32 v[78:79], v[78:79], v[192:193], v[208:209]
	v_cvt_pk_bf16_f32 v76, v76, v77
	v_cvt_pk_bf16_f32 v77, v78, v79
	global_store_dwordx2 v227, v[76:77], s[56:57] offset:1536
	s_add_u32 s56, s56, 0x4000
	s_addc_u32 s57, s57, 0
	v_pk_mul_f32 v[80:81], v[80:81], v[220:221] op_sel_hi:[1,0]
	v_pk_mul_f32 v[82:83], v[82:83], v[220:221] op_sel_hi:[1,0]
	v_pk_fma_f32 v[80:81], v[80:81], v[178:179], v[194:195]
	v_pk_fma_f32 v[82:83], v[82:83], v[180:181], v[196:197]
	v_cvt_pk_bf16_f32 v80, v80, v81
	v_cvt_pk_bf16_f32 v81, v82, v83
	global_store_dwordx2 v227, v[80:81], s[56:57]
	v_pk_mul_f32 v[84:85], v[84:85], v[220:221] op_sel_hi:[1,0]
	v_pk_mul_f32 v[86:87], v[86:87], v[220:221] op_sel_hi:[1,0]
	v_pk_fma_f32 v[84:85], v[84:85], v[182:183], v[198:199]
	v_pk_fma_f32 v[86:87], v[86:87], v[184:185], v[200:201]
	v_cvt_pk_bf16_f32 v84, v84, v85
	v_cvt_pk_bf16_f32 v85, v86, v87
	global_store_dwordx2 v227, v[84:85], s[56:57] offset:512
	v_pk_mul_f32 v[88:89], v[88:89], v[220:221] op_sel_hi:[1,0]
	v_pk_mul_f32 v[90:91], v[90:91], v[220:221] op_sel_hi:[1,0]
	v_pk_fma_f32 v[88:89], v[88:89], v[186:187], v[202:203]
	v_pk_fma_f32 v[90:91], v[90:91], v[188:189], v[204:205]
	v_cvt_pk_bf16_f32 v88, v88, v89
	v_cvt_pk_bf16_f32 v89, v90, v91
	global_store_dwordx2 v227, v[88:89], s[56:57] offset:1024
	v_pk_mul_f32 v[92:93], v[92:93], v[220:221] op_sel_hi:[1,0]
	v_pk_mul_f32 v[94:95], v[94:95], v[220:221] op_sel_hi:[1,0]
	v_pk_fma_f32 v[92:93], v[92:93], v[190:191], v[206:207]
	v_pk_fma_f32 v[94:95], v[94:95], v[192:193], v[208:209]
	v_cvt_pk_bf16_f32 v92, v92, v93
	v_cvt_pk_bf16_f32 v93, v94, v95
	global_store_dwordx2 v227, v[92:93], s[56:57] offset:1536
	s_add_u32 s56, s56, 0x4000
	s_addc_u32 s57, s57, 0
	v_pk_mul_f32 v[134:135], v[134:135], v[222:223] op_sel_hi:[1,0]
	v_pk_mul_f32 v[136:137], v[136:137], v[222:223] op_sel_hi:[1,0]
	v_pk_fma_f32 v[134:135], v[134:135], v[178:179], v[194:195]
	v_pk_fma_f32 v[136:137], v[136:137], v[180:181], v[196:197]
	v_cvt_pk_bf16_f32 v134, v134, v135
	v_cvt_pk_bf16_f32 v135, v136, v137
	global_store_dwordx2 v227, v[134:135], s[56:57]
	v_pk_mul_f32 v[138:139], v[138:139], v[222:223] op_sel_hi:[1,0]
	v_pk_mul_f32 v[140:141], v[140:141], v[222:223] op_sel_hi:[1,0]
	v_pk_fma_f32 v[138:139], v[138:139], v[182:183], v[198:199]
	v_pk_fma_f32 v[140:141], v[140:141], v[184:185], v[200:201]
	v_cvt_pk_bf16_f32 v138, v138, v139
	v_cvt_pk_bf16_f32 v139, v140, v141
	global_store_dwordx2 v227, v[138:139], s[56:57] offset:512
	v_pk_mul_f32 v[142:143], v[142:143], v[222:223] op_sel_hi:[1,0]
	v_pk_mul_f32 v[144:145], v[144:145], v[222:223] op_sel_hi:[1,0]
	v_pk_fma_f32 v[142:143], v[142:143], v[186:187], v[202:203]
	v_pk_fma_f32 v[144:145], v[144:145], v[188:189], v[204:205]
	v_cvt_pk_bf16_f32 v142, v142, v143
	v_cvt_pk_bf16_f32 v143, v144, v145
	global_store_dwordx2 v227, v[142:143], s[56:57] offset:1024
	v_pk_mul_f32 v[146:147], v[146:147], v[222:223] op_sel_hi:[1,0]
	v_pk_mul_f32 v[148:149], v[148:149], v[222:223] op_sel_hi:[1,0]
	v_pk_fma_f32 v[146:147], v[146:147], v[190:191], v[206:207]
	v_pk_fma_f32 v[148:149], v[148:149], v[192:193], v[208:209]
	v_cvt_pk_bf16_f32 v146, v146, v147
	v_cvt_pk_bf16_f32 v147, v148, v149
	global_store_dwordx2 v227, v[146:147], s[56:57] offset:1536
	s_add_u32 s56, s56, 0x4000
	s_addc_u32 s57, s57, 0
	v_pk_mul_f32 v[150:151], v[150:151], v[224:225] op_sel_hi:[1,0]
	v_pk_mul_f32 v[152:153], v[152:153], v[224:225] op_sel_hi:[1,0]
	v_pk_fma_f32 v[150:151], v[150:151], v[178:179], v[194:195]
	v_pk_fma_f32 v[152:153], v[152:153], v[180:181], v[196:197]
	v_cvt_pk_bf16_f32 v150, v150, v151
	v_cvt_pk_bf16_f32 v151, v152, v153
	global_store_dwordx2 v227, v[150:151], s[56:57]
	v_pk_mul_f32 v[154:155], v[154:155], v[224:225] op_sel_hi:[1,0]
	v_pk_mul_f32 v[156:157], v[156:157], v[224:225] op_sel_hi:[1,0]
	v_pk_fma_f32 v[154:155], v[154:155], v[182:183], v[198:199]
	v_pk_fma_f32 v[156:157], v[156:157], v[184:185], v[200:201]
	v_cvt_pk_bf16_f32 v154, v154, v155
	v_cvt_pk_bf16_f32 v155, v156, v157
	global_store_dwordx2 v227, v[154:155], s[56:57] offset:512
	v_pk_mul_f32 v[158:159], v[158:159], v[224:225] op_sel_hi:[1,0]
	v_pk_mul_f32 v[160:161], v[160:161], v[224:225] op_sel_hi:[1,0]
	v_pk_fma_f32 v[158:159], v[158:159], v[186:187], v[202:203]
	v_pk_fma_f32 v[160:161], v[160:161], v[188:189], v[204:205]
	v_cvt_pk_bf16_f32 v158, v158, v159
	v_cvt_pk_bf16_f32 v159, v160, v161
	global_store_dwordx2 v227, v[158:159], s[56:57] offset:1024
	v_pk_mul_f32 v[162:163], v[162:163], v[224:225] op_sel_hi:[1,0]
	v_pk_mul_f32 v[164:165], v[164:165], v[224:225] op_sel_hi:[1,0]
	v_pk_fma_f32 v[162:163], v[162:163], v[190:191], v[206:207]
	v_pk_fma_f32 v[164:165], v[164:165], v[192:193], v[208:209]
	v_cvt_pk_bf16_f32 v162, v162, v163
	v_cvt_pk_bf16_f32 v163, v164, v165
	global_store_dwordx2 v227, v[162:163], s[56:57] offset:1536

.LBB0_1848:
	s_or_b64 exec, exec, s[20:21]
	s_sext_i32_i8 s13, s30
	s_lshl_b32 s12, s12, 8
	s_lshl_b32 s13, s13, 6
	s_add_i32 s36, s12, s13
	v_mov_b32_e32 v1, v170
	s_barrier
	s_load_dwordx2 s[52:53], s[0:1], 0xe8
	s_mov_b32 s66, s36
	v_readfirstlane_b32 s65, v170
	v_and_b32_e32 v226, 63, v170
	v_mov_b32_e32 v228, 0x358637bd
	v_lshlrev_b32_e32 v227, 3, v226
	v_lshlrev_b32_e32 v226, 4, v226
	s_lshr_b32 s65, s65, 6
	s_add_i32 s66, s66, s65
	s_waitcnt lgkmcnt(0)
	s_sub_i32 s67, s66, 0x1000
	s_ashr_i32 s67, s67, 11
	s_add_i32 s67, s67, 1
	s_cmp_gt_i32 s66, 0xfff
	s_cselect_b32 s67, s67, 0
	s_add_i32 s67, s67, 5
	s_mul_i32 s67, s67, 6
	s_add_i32 s67, s67, 3
	s_lshl_b32 s67, s67, 12
	s_add_u32 s58, s52, 0x780000
	s_addc_u32 s59, s53, 0
	s_add_u32 s58, s58, s67
	s_addc_u32 s59, s59, 0
	s_add_u32 s60, s58, 0x1000
	s_addc_u32 s61, s59, 0
	global_load_dwordx4 v[178:181], v226, s[58:59]
	global_load_dwordx4 v[182:185], v226, s[58:59] offset:1024
	global_load_dwordx4 v[186:189], v226, s[58:59] offset:2048
	global_load_dwordx4 v[190:193], v226, s[58:59] offset:3072
	global_load_dwordx4 v[194:197], v226, s[60:61]
	global_load_dwordx4 v[198:201], v226, s[60:61] offset:1024
	global_load_dwordx4 v[202:205], v226, s[60:61] offset:2048
	global_load_dwordx4 v[206:209], v226, s[60:61] offset:3072
	s_lshl_b32 s67, s66, 11
	s_add_u32 s56, s52, 0x2ebc000
	s_addc_u32 s57, s53, 0
	s_add_u32 s56, s56, s67
	s_addc_u32 s57, s57, 0
	s_lshl_b32 s67, s66, 12
	s_add_u32 s54, s52, 0x46bc000
	s_addc_u32 s55, s53, 0
	s_add_u32 s54, s54, s67
	s_addc_u32 s55, s55, 0
	global_load_dwordx4 v[0:3], v226, s[54:55]
	global_load_dwordx4 v[4:7], v226, s[54:55] offset:1024
	global_load_dwordx4 v[8:11], v226, s[54:55] offset:2048
	global_load_dwordx4 v[12:15], v226, s[54:55] offset:3072
	s_add_u32 s54, s54, 0x8000
	s_addc_u32 s55, s55, 0
	global_load_dwordx4 v[16:19], v226, s[54:55]
	global_load_dwordx4 v[20:23], v226, s[54:55] offset:1024
	global_load_dwordx4 v[24:27], v226, s[54:55] offset:2048
	global_load_dwordx4 v[28:31], v226, s[54:55] offset:3072
	s_add_u32 s54, s54, 0x8000
	s_addc_u32 s55, s55, 0
	global_load_dwordx4 v[32:35], v226, s[54:55]
	global_load_dwordx4 v[36:39], v226, s[54:55] offset:1024
	global_load_dwordx4 v[40:43], v226, s[54:55] offset:2048
	global_load_dwordx4 v[44:47], v226, s[54:55] offset:3072
	s_add_u32 s54, s54, 0x8000
	s_addc_u32 s55, s55, 0
	global_load_dwordx4 v[48:51], v226, s[54:55]
	global_load_dwordx4 v[52:55], v226, s[54:55] offset:1024
	global_load_dwordx4 v[56:59], v226, s[54:55] offset:2048
	global_load_dwordx4 v[60:63], v226, s[54:55] offset:3072
	s_add_u32 s54, s54, 0x8000
	s_addc_u32 s55, s55, 0
	global_load_dwordx4 v[64:67], v226, s[54:55]
	global_load_dwordx4 v[68:71], v226, s[54:55] offset:1024
	global_load_dwordx4 v[72:75], v226, s[54:55] offset:2048
	global_load_dwordx4 v[76:79], v226, s[54:55] offset:3072
	s_add_u32 s54, s54, 0x8000
	s_addc_u32 s55, s55, 0
	global_load_dwordx4 v[80:83], v226, s[54:55]
	global_load_dwordx4 v[84:87], v226, s[54:55] offset:1024
	global_load_dwordx4 v[88:91], v226, s[54:55] offset:2048
	global_load_dwordx4 v[92:95], v226, s[54:55] offset:3072
	s_add_u32 s54, s54, 0x8000
	s_addc_u32 s55, s55, 0
	global_load_dwordx4 v[134:137], v226, s[54:55]
	global_load_dwordx4 v[138:141], v226, s[54:55] offset:1024
	global_load_dwordx4 v[142:145], v226, s[54:55] offset:2048
	global_load_dwordx4 v[146:149], v226, s[54:55] offset:3072
	s_add_u32 s54, s54, 0x8000
	s_addc_u32 s55, s55, 0
	global_load_dwordx4 v[150:153], v226, s[54:55]
	global_load_dwordx4 v[154:157], v226, s[54:55] offset:1024
	global_load_dwordx4 v[158:161], v226, s[54:55] offset:2048
	global_load_dwordx4 v[162:165], v226, s[54:55] offset:3072
	s_waitcnt vmcnt(28)
	v_mul_f32_e32 v210, v0, v0
	v_fmac_f32_e32 v210, v1, v1
	v_fmac_f32_e32 v210, v2, v2
	v_fmac_f32_e32 v210, v3, v3
	v_fmac_f32_e32 v210, v4, v4
	v_fmac_f32_e32 v210, v5, v5
	v_fmac_f32_e32 v210, v6, v6
	v_fmac_f32_e32 v210, v7, v7
	v_fmac_f32_e32 v210, v8, v8
	v_fmac_f32_e32 v210, v9, v9
	v_fmac_f32_e32 v210, v10, v10
	v_fmac_f32_e32 v210, v11, v11
	v_fmac_f32_e32 v210, v12, v12
	v_fmac_f32_e32 v210, v13, v13
	v_fmac_f32_e32 v210, v14, v14
	v_fmac_f32_e32 v210, v15, v15
	s_waitcnt vmcnt(24)
	v_mul_f32_e32 v212, v16, v16
	v_fmac_f32_e32 v212, v17, v17
	v_fmac_f32_e32 v212, v18, v18
	v_fmac_f32_e32 v212, v19, v19
	v_fmac_f32_e32 v212, v20, v20
	v_fmac_f32_e32 v212, v21, v21
	v_fmac_f32_e32 v212, v22, v22
	v_fmac_f32_e32 v212, v23, v23
	v_fmac_f32_e32 v212, v24, v24
	v_fmac_f32_e32 v212, v25, v25
	v_fmac_f32_e32 v212, v26, v26
	v_fmac_f32_e32 v212, v27, v27
	v_fmac_f32_e32 v212, v28, v28
	v_fmac_f32_e32 v212, v29, v29
	v_fmac_f32_e32 v212, v30, v30
	v_fmac_f32_e32 v212, v31, v31
	s_waitcnt vmcnt(20)
	v_mul_f32_e32 v214, v32, v32
	v_fmac_f32_e32 v214, v33, v33
	v_fmac_f32_e32 v214, v34, v34
	v_fmac_f32_e32 v214, v35, v35
	v_fmac_f32_e32 v214, v36, v36
	v_fmac_f32_e32 v214, v37, v37
	v_fmac_f32_e32 v214, v38, v38
	v_fmac_f32_e32 v214, v39, v39
	v_fmac_f32_e32 v214, v40, v40
	v_fmac_f32_e32 v214, v41, v41
	v_fmac_f32_e32 v214, v42, v42
	v_fmac_f32_e32 v214, v43, v43
	v_fmac_f32_e32 v214, v44, v44
	v_fmac_f32_e32 v214, v45, v45
	v_fmac_f32_e32 v214, v46, v46
	v_fmac_f32_e32 v214, v47, v47
	s_waitcnt vmcnt(16)
	v_mul_f32_e32 v216, v48, v48
	v_fmac_f32_e32 v216, v49, v49
	v_fmac_f32_e32 v216, v50, v50
	v_fmac_f32_e32 v216, v51, v51
	v_fmac_f32_e32 v216, v52, v52
	v_fmac_f32_e32 v216, v53, v53
	v_fmac_f32_e32 v216, v54, v54
	v_fmac_f32_e32 v216, v55, v55
	v_fmac_f32_e32 v216, v56, v56
	v_fmac_f32_e32 v216, v57, v57
	v_fmac_f32_e32 v216, v58, v58
	v_fmac_f32_e32 v216, v59, v59
	v_fmac_f32_e32 v216, v60, v60
	v_fmac_f32_e32 v216, v61, v61
	v_fmac_f32_e32 v216, v62, v62
	v_fmac_f32_e32 v216, v63, v63
	s_waitcnt vmcnt(12)
	v_mul_f32_e32 v218, v64, v64
	v_fmac_f32_e32 v218, v65, v65
	v_fmac_f32_e32 v218, v66, v66
	v_fmac_f32_e32 v218, v67, v67
	v_fmac_f32_e32 v218, v68, v68
	v_fmac_f32_e32 v218, v69, v69
	v_fmac_f32_e32 v218, v70, v70
	v_fmac_f32_e32 v218, v71, v71
	v_fmac_f32_e32 v218, v72, v72
	v_fmac_f32_e32 v218, v73, v73
	v_fmac_f32_e32 v218, v74, v74
	v_fmac_f32_e32 v218, v75, v75
	v_fmac_f32_e32 v218, v76, v76
	v_fmac_f32_e32 v218, v77, v77
	v_fmac_f32_e32 v218, v78, v78
	v_fmac_f32_e32 v218, v79, v79
	s_waitcnt vmcnt(8)
	v_mul_f32_e32 v220, v80, v80
	v_fmac_f32_e32 v220, v81, v81
	v_fmac_f32_e32 v220, v82, v82
	v_fmac_f32_e32 v220, v83, v83
	v_fmac_f32_e32 v220, v84, v84
	v_fmac_f32_e32 v220, v85, v85
	v_fmac_f32_e32 v220, v86, v86
	v_fmac_f32_e32 v220, v87, v87
	v_fmac_f32_e32 v220, v88, v88
	v_fmac_f32_e32 v220, v89, v89
	v_fmac_f32_e32 v220, v90, v90
	v_fmac_f32_e32 v220, v91, v91
	v_fmac_f32_e32 v220, v92, v92
	v_fmac_f32_e32 v220, v93, v93
	v_fmac_f32_e32 v220, v94, v94
	v_fmac_f32_e32 v220, v95, v95
	s_waitcnt vmcnt(4)
	v_mul_f32_e32 v222, v134, v134
	v_fmac_f32_e32 v222, v135, v135
	v_fmac_f32_e32 v222, v136, v136
	v_fmac_f32_e32 v222, v137, v137
	v_fmac_f32_e32 v222, v138, v138
	v_fmac_f32_e32 v222, v139, v139
	v_fmac_f32_e32 v222, v140, v140
	v_fmac_f32_e32 v222, v141, v141
	v_fmac_f32_e32 v222, v142, v142
	v_fmac_f32_e32 v222, v143, v143
	v_fmac_f32_e32 v222, v144, v144
	v_fmac_f32_e32 v222, v145, v145
	v_fmac_f32_e32 v222, v146, v146
	v_fmac_f32_e32 v222, v147, v147
	v_fmac_f32_e32 v222, v148, v148
	v_fmac_f32_e32 v222, v149, v149
	s_waitcnt vmcnt(0)
	v_mul_f32_e32 v224, v150, v150
	v_fmac_f32_e32 v224, v151, v151
	v_fmac_f32_e32 v224, v152, v152
	v_fmac_f32_e32 v224, v153, v153
	v_fmac_f32_e32 v224, v154, v154
	v_fmac_f32_e32 v224, v155, v155
	v_fmac_f32_e32 v224, v156, v156
	v_fmac_f32_e32 v224, v157, v157
	v_fmac_f32_e32 v224, v158, v158
	v_fmac_f32_e32 v224, v159, v159
	v_fmac_f32_e32 v224, v160, v160
	v_fmac_f32_e32 v224, v161, v161
	v_fmac_f32_e32 v224, v162, v162
	v_fmac_f32_e32 v224, v163, v163
	v_fmac_f32_e32 v224, v164, v164
	v_fmac_f32_e32 v224, v165, v165
	ds_bpermute_b32 v211, v171, v210
	ds_bpermute_b32 v213, v171, v212
	ds_bpermute_b32 v215, v171, v214
	ds_bpermute_b32 v217, v171, v216
	ds_bpermute_b32 v219, v171, v218
	ds_bpermute_b32 v221, v171, v220
	ds_bpermute_b32 v223, v171, v222
	ds_bpermute_b32 v225, v171, v224
	s_waitcnt lgkmcnt(7)
	v_add_f32_e32 v210, v210, v211
	s_waitcnt lgkmcnt(6)
	v_add_f32_e32 v212, v212, v213
	s_waitcnt lgkmcnt(5)
	v_add_f32_e32 v214, v214, v215
	s_waitcnt lgkmcnt(4)
	v_add_f32_e32 v216, v216, v217
	s_waitcnt lgkmcnt(3)
	v_add_f32_e32 v218, v218, v219
	s_waitcnt lgkmcnt(2)
	v_add_f32_e32 v220, v220, v221
	s_waitcnt lgkmcnt(1)
	v_add_f32_e32 v222, v222, v223
	s_waitcnt lgkmcnt(0)
	v_add_f32_e32 v224, v224, v225
	ds_bpermute_b32 v211, v172, v210
	ds_bpermute_b32 v213, v172, v212
	ds_bpermute_b32 v215, v172, v214
	ds_bpermute_b32 v217, v172, v216
	ds_bpermute_b32 v219, v172, v218
	ds_bpermute_b32 v221, v172, v220
	ds_bpermute_b32 v223, v172, v222
	ds_bpermute_b32 v225, v172, v224
	s_waitcnt lgkmcnt(7)
	v_add_f32_e32 v210, v210, v211
	s_waitcnt lgkmcnt(6)
	v_add_f32_e32 v212, v212, v213
	s_waitcnt lgkmcnt(5)
	v_add_f32_e32 v214, v214, v215
	s_waitcnt lgkmcnt(4)
	v_add_f32_e32 v216, v216, v217
	s_waitcnt lgkmcnt(3)
	v_add_f32_e32 v218, v218, v219
	s_waitcnt lgkmcnt(2)
	v_add_f32_e32 v220, v220, v221
	s_waitcnt lgkmcnt(1)
	v_add_f32_e32 v222, v222, v223
	s_waitcnt lgkmcnt(0)
	v_add_f32_e32 v224, v224, v225
	ds_bpermute_b32 v211, v173, v210
	ds_bpermute_b32 v213, v173, v212
	ds_bpermute_b32 v215, v173, v214
	ds_bpermute_b32 v217, v173, v216
	ds_bpermute_b32 v219, v173, v218
	ds_bpermute_b32 v221, v173, v220
	ds_bpermute_b32 v223, v173, v222
	ds_bpermute_b32 v225, v173, v224
	s_waitcnt lgkmcnt(7)
	v_add_f32_e32 v210, v210, v211
	s_waitcnt lgkmcnt(6)
	v_add_f32_e32 v212, v212, v213
	s_waitcnt lgkmcnt(5)
	v_add_f32_e32 v214, v214, v215
	s_waitcnt lgkmcnt(4)
	v_add_f32_e32 v216, v216, v217
	s_waitcnt lgkmcnt(3)
	v_add_f32_e32 v218, v218, v219
	s_waitcnt lgkmcnt(2)
	v_add_f32_e32 v220, v220, v221
	s_waitcnt lgkmcnt(1)
	v_add_f32_e32 v222, v222, v223
	s_waitcnt lgkmcnt(0)
	v_add_f32_e32 v224, v224, v225
	ds_bpermute_b32 v211, v174, v210
	ds_bpermute_b32 v213, v174, v212
	ds_bpermute_b32 v215, v174, v214
	ds_bpermute_b32 v217, v174, v216
	ds_bpermute_b32 v219, v174, v218
	ds_bpermute_b32 v221, v174, v220
	ds_bpermute_b32 v223, v174, v222
	ds_bpermute_b32 v225, v174, v224
	s_waitcnt lgkmcnt(7)
	v_add_f32_e32 v210, v210, v211
	s_waitcnt lgkmcnt(6)
	v_add_f32_e32 v212, v212, v213
	s_waitcnt lgkmcnt(5)
	v_add_f32_e32 v214, v214, v215
	s_waitcnt lgkmcnt(4)
	v_add_f32_e32 v216, v216, v217
	s_waitcnt lgkmcnt(3)
	v_add_f32_e32 v218, v218, v219
	s_waitcnt lgkmcnt(2)
	v_add_f32_e32 v220, v220, v221
	s_waitcnt lgkmcnt(1)
	v_add_f32_e32 v222, v222, v223
	s_waitcnt lgkmcnt(0)
	v_add_f32_e32 v224, v224, v225
	ds_bpermute_b32 v211, v175, v210
	ds_bpermute_b32 v213, v175, v212
	ds_bpermute_b32 v215, v175, v214
	ds_bpermute_b32 v217, v175, v216
	ds_bpermute_b32 v219, v175, v218
	ds_bpermute_b32 v221, v175, v220
	ds_bpermute_b32 v223, v175, v222
	ds_bpermute_b32 v225, v175, v224
	s_waitcnt lgkmcnt(7)
	v_add_f32_e32 v210, v210, v211
	s_waitcnt lgkmcnt(6)
	v_add_f32_e32 v212, v212, v213
	s_waitcnt lgkmcnt(5)
	v_add_f32_e32 v214, v214, v215
	s_waitcnt lgkmcnt(4)
	v_add_f32_e32 v216, v216, v217
	s_waitcnt lgkmcnt(3)
	v_add_f32_e32 v218, v218, v219
	s_waitcnt lgkmcnt(2)
	v_add_f32_e32 v220, v220, v221
	s_waitcnt lgkmcnt(1)
	v_add_f32_e32 v222, v222, v223
	s_waitcnt lgkmcnt(0)
	v_add_f32_e32 v224, v224, v225
	ds_bpermute_b32 v211, v176, v210
	ds_bpermute_b32 v213, v176, v212
	ds_bpermute_b32 v215, v176, v214
	ds_bpermute_b32 v217, v176, v216
	ds_bpermute_b32 v219, v176, v218
	ds_bpermute_b32 v221, v176, v220
	ds_bpermute_b32 v223, v176, v222
	ds_bpermute_b32 v225, v176, v224
	s_waitcnt lgkmcnt(7)
	v_add_f32_e32 v210, v210, v211
	s_waitcnt lgkmcnt(6)
	v_add_f32_e32 v212, v212, v213
	s_waitcnt lgkmcnt(5)
	v_add_f32_e32 v214, v214, v215
	s_waitcnt lgkmcnt(4)
	v_add_f32_e32 v216, v216, v217
	s_waitcnt lgkmcnt(3)
	v_add_f32_e32 v218, v218, v219
	s_waitcnt lgkmcnt(2)
	v_add_f32_e32 v220, v220, v221
	s_waitcnt lgkmcnt(1)
	v_add_f32_e32 v222, v222, v223
	s_waitcnt lgkmcnt(0)
	v_add_f32_e32 v224, v224, v225
	v_fmamk_f32 v210, v210, 0x3a800000, v228
	v_fmamk_f32 v212, v212, 0x3a800000, v228
	v_fmamk_f32 v214, v214, 0x3a800000, v228
	v_fmamk_f32 v216, v216, 0x3a800000, v228
	v_fmamk_f32 v218, v218, 0x3a800000, v228
	v_fmamk_f32 v220, v220, 0x3a800000, v228
	v_fmamk_f32 v222, v222, 0x3a800000, v228
	v_fmamk_f32 v224, v224, 0x3a800000, v228
	v_rsq_f32_e32 v210, v210
	v_rsq_f32_e32 v212, v212
	v_rsq_f32_e32 v214, v214
	v_rsq_f32_e32 v216, v216
	v_rsq_f32_e32 v218, v218
	v_rsq_f32_e32 v220, v220
	v_rsq_f32_e32 v222, v222
	v_rsq_f32_e32 v224, v224
	v_pk_mul_f32 v[0:1], v[0:1], v[210:211] op_sel_hi:[1,0]
	v_pk_mul_f32 v[2:3], v[2:3], v[210:211] op_sel_hi:[1,0]
	v_pk_fma_f32 v[0:1], v[0:1], v[178:179], v[194:195]
	v_pk_fma_f32 v[2:3], v[2:3], v[180:181], v[196:197]
	v_cvt_pk_bf16_f32 v0, v0, v1
	v_cvt_pk_bf16_f32 v1, v2, v3
	global_store_dwordx2 v227, v[0:1], s[56:57]
	v_pk_mul_f32 v[4:5], v[4:5], v[210:211] op_sel_hi:[1,0]
	v_pk_mul_f32 v[6:7], v[6:7], v[210:211] op_sel_hi:[1,0]
	v_pk_fma_f32 v[4:5], v[4:5], v[182:183], v[198:199]
	v_pk_fma_f32 v[6:7], v[6:7], v[184:185], v[200:201]
	v_cvt_pk_bf16_f32 v4, v4, v5
	v_cvt_pk_bf16_f32 v5, v6, v7
	global_store_dwordx2 v227, v[4:5], s[56:57] offset:512
	v_pk_mul_f32 v[8:9], v[8:9], v[210:211] op_sel_hi:[1,0]
	v_pk_mul_f32 v[10:11], v[10:11], v[210:211] op_sel_hi:[1,0]
	v_pk_fma_f32 v[8:9], v[8:9], v[186:187], v[202:203]
	v_pk_fma_f32 v[10:11], v[10:11], v[188:189], v[204:205]
	v_cvt_pk_bf16_f32 v8, v8, v9
	v_cvt_pk_bf16_f32 v9, v10, v11
	global_store_dwordx2 v227, v[8:9], s[56:57] offset:1024
	v_pk_mul_f32 v[12:13], v[12:13], v[210:211] op_sel_hi:[1,0]
	v_pk_mul_f32 v[14:15], v[14:15], v[210:211] op_sel_hi:[1,0]
	v_pk_fma_f32 v[12:13], v[12:13], v[190:191], v[206:207]
	v_pk_fma_f32 v[14:15], v[14:15], v[192:193], v[208:209]
	v_cvt_pk_bf16_f32 v12, v12, v13
	v_cvt_pk_bf16_f32 v13, v14, v15
	global_store_dwordx2 v227, v[12:13], s[56:57] offset:1536
	s_add_u32 s56, s56, 0x4000
	s_addc_u32 s57, s57, 0
	v_pk_mul_f32 v[16:17], v[16:17], v[212:213] op_sel_hi:[1,0]
	v_pk_mul_f32 v[18:19], v[18:19], v[212:213] op_sel_hi:[1,0]
	v_pk_fma_f32 v[16:17], v[16:17], v[178:179], v[194:195]
	v_pk_fma_f32 v[18:19], v[18:19], v[180:181], v[196:197]
	v_cvt_pk_bf16_f32 v16, v16, v17
	v_cvt_pk_bf16_f32 v17, v18, v19
	global_store_dwordx2 v227, v[16:17], s[56:57]
	v_pk_mul_f32 v[20:21], v[20:21], v[212:213] op_sel_hi:[1,0]
	v_pk_mul_f32 v[22:23], v[22:23], v[212:213] op_sel_hi:[1,0]
	v_pk_fma_f32 v[20:21], v[20:21], v[182:183], v[198:199]
	v_pk_fma_f32 v[22:23], v[22:23], v[184:185], v[200:201]
	v_cvt_pk_bf16_f32 v20, v20, v21
	v_cvt_pk_bf16_f32 v21, v22, v23
	global_store_dwordx2 v227, v[20:21], s[56:57] offset:512
	v_pk_mul_f32 v[24:25], v[24:25], v[212:213] op_sel_hi:[1,0]
	v_pk_mul_f32 v[26:27], v[26:27], v[212:213] op_sel_hi:[1,0]
	v_pk_fma_f32 v[24:25], v[24:25], v[186:187], v[202:203]
	v_pk_fma_f32 v[26:27], v[26:27], v[188:189], v[204:205]
	v_cvt_pk_bf16_f32 v24, v24, v25
	v_cvt_pk_bf16_f32 v25, v26, v27
	global_store_dwordx2 v227, v[24:25], s[56:57] offset:1024
	v_pk_mul_f32 v[28:29], v[28:29], v[212:213] op_sel_hi:[1,0]
	v_pk_mul_f32 v[30:31], v[30:31], v[212:213] op_sel_hi:[1,0]
	v_pk_fma_f32 v[28:29], v[28:29], v[190:191], v[206:207]
	v_pk_fma_f32 v[30:31], v[30:31], v[192:193], v[208:209]
	v_cvt_pk_bf16_f32 v28, v28, v29
	v_cvt_pk_bf16_f32 v29, v30, v31
	global_store_dwordx2 v227, v[28:29], s[56:57] offset:1536
	s_add_u32 s56, s56, 0x4000
	s_addc_u32 s57, s57, 0
	v_pk_mul_f32 v[32:33], v[32:33], v[214:215] op_sel_hi:[1,0]
	v_pk_mul_f32 v[34:35], v[34:35], v[214:215] op_sel_hi:[1,0]
	v_pk_fma_f32 v[32:33], v[32:33], v[178:179], v[194:195]
	v_pk_fma_f32 v[34:35], v[34:35], v[180:181], v[196:197]
	v_cvt_pk_bf16_f32 v32, v32, v33
	v_cvt_pk_bf16_f32 v33, v34, v35
	global_store_dwordx2 v227, v[32:33], s[56:57]
	v_pk_mul_f32 v[36:37], v[36:37], v[214:215] op_sel_hi:[1,0]
	v_pk_mul_f32 v[38:39], v[38:39], v[214:215] op_sel_hi:[1,0]
	v_pk_fma_f32 v[36:37], v[36:37], v[182:183], v[198:199]
	v_pk_fma_f32 v[38:39], v[38:39], v[184:185], v[200:201]
	v_cvt_pk_bf16_f32 v36, v36, v37
	v_cvt_pk_bf16_f32 v37, v38, v39
	global_store_dwordx2 v227, v[36:37], s[56:57] offset:512
	v_pk_mul_f32 v[40:41], v[40:41], v[214:215] op_sel_hi:[1,0]
	v_pk_mul_f32 v[42:43], v[42:43], v[214:215] op_sel_hi:[1,0]
	v_pk_fma_f32 v[40:41], v[40:41], v[186:187], v[202:203]
	v_pk_fma_f32 v[42:43], v[42:43], v[188:189], v[204:205]
	v_cvt_pk_bf16_f32 v40, v40, v41
	v_cvt_pk_bf16_f32 v41, v42, v43
	global_store_dwordx2 v227, v[40:41], s[56:57] offset:1024
	v_pk_mul_f32 v[44:45], v[44:45], v[214:215] op_sel_hi:[1,0]
	v_pk_mul_f32 v[46:47], v[46:47], v[214:215] op_sel_hi:[1,0]
	v_pk_fma_f32 v[44:45], v[44:45], v[190:191], v[206:207]
	v_pk_fma_f32 v[46:47], v[46:47], v[192:193], v[208:209]
	v_cvt_pk_bf16_f32 v44, v44, v45
	v_cvt_pk_bf16_f32 v45, v46, v47
	global_store_dwordx2 v227, v[44:45], s[56:57] offset:1536
	s_add_u32 s56, s56, 0x4000
	s_addc_u32 s57, s57, 0
	v_pk_mul_f32 v[48:49], v[48:49], v[216:217] op_sel_hi:[1,0]
	v_pk_mul_f32 v[50:51], v[50:51], v[216:217] op_sel_hi:[1,0]
	v_pk_fma_f32 v[48:49], v[48:49], v[178:179], v[194:195]
	v_pk_fma_f32 v[50:51], v[50:51], v[180:181], v[196:197]
	v_cvt_pk_bf16_f32 v48, v48, v49
	v_cvt_pk_bf16_f32 v49, v50, v51
	global_store_dwordx2 v227, v[48:49], s[56:57]
	v_pk_mul_f32 v[52:53], v[52:53], v[216:217] op_sel_hi:[1,0]
	v_pk_mul_f32 v[54:55], v[54:55], v[216:217] op_sel_hi:[1,0]
	v_pk_fma_f32 v[52:53], v[52:53], v[182:183], v[198:199]
	v_pk_fma_f32 v[54:55], v[54:55], v[184:185], v[200:201]
	v_cvt_pk_bf16_f32 v52, v52, v53
	v_cvt_pk_bf16_f32 v53, v54, v55
	global_store_dwordx2 v227, v[52:53], s[56:57] offset:512
	v_pk_mul_f32 v[56:57], v[56:57], v[216:217] op_sel_hi:[1,0]
	v_pk_mul_f32 v[58:59], v[58:59], v[216:217] op_sel_hi:[1,0]
	v_pk_fma_f32 v[56:57], v[56:57], v[186:187], v[202:203]
	v_pk_fma_f32 v[58:59], v[58:59], v[188:189], v[204:205]
	v_cvt_pk_bf16_f32 v56, v56, v57
	v_cvt_pk_bf16_f32 v57, v58, v59
	global_store_dwordx2 v227, v[56:57], s[56:57] offset:1024
	v_pk_mul_f32 v[60:61], v[60:61], v[216:217] op_sel_hi:[1,0]
	v_pk_mul_f32 v[62:63], v[62:63], v[216:217] op_sel_hi:[1,0]
	v_pk_fma_f32 v[60:61], v[60:61], v[190:191], v[206:207]
	v_pk_fma_f32 v[62:63], v[62:63], v[192:193], v[208:209]
	v_cvt_pk_bf16_f32 v60, v60, v61
	v_cvt_pk_bf16_f32 v61, v62, v63
	global_store_dwordx2 v227, v[60:61], s[56:57] offset:1536
	s_add_u32 s56, s56, 0x4000
	s_addc_u32 s57, s57, 0
	v_pk_mul_f32 v[64:65], v[64:65], v[218:219] op_sel_hi:[1,0]
	v_pk_mul_f32 v[66:67], v[66:67], v[218:219] op_sel_hi:[1,0]
	v_pk_fma_f32 v[64:65], v[64:65], v[178:179], v[194:195]
	v_pk_fma_f32 v[66:67], v[66:67], v[180:181], v[196:197]
	v_cvt_pk_bf16_f32 v64, v64, v65
	v_cvt_pk_bf16_f32 v65, v66, v67
	global_store_dwordx2 v227, v[64:65], s[56:57]
	v_pk_mul_f32 v[68:69], v[68:69], v[218:219] op_sel_hi:[1,0]
	v_pk_mul_f32 v[70:71], v[70:71], v[218:219] op_sel_hi:[1,0]
	v_pk_fma_f32 v[68:69], v[68:69], v[182:183], v[198:199]
	v_pk_fma_f32 v[70:71], v[70:71], v[184:185], v[200:201]
	v_cvt_pk_bf16_f32 v68, v68, v69
	v_cvt_pk_bf16_f32 v69, v70, v71
	global_store_dwordx2 v227, v[68:69], s[56:57] offset:512
	v_pk_mul_f32 v[72:73], v[72:73], v[218:219] op_sel_hi:[1,0]
	v_pk_mul_f32 v[74:75], v[74:75], v[218:219] op_sel_hi:[1,0]
	v_pk_fma_f32 v[72:73], v[72:73], v[186:187], v[202:203]
	v_pk_fma_f32 v[74:75], v[74:75], v[188:189], v[204:205]
	v_cvt_pk_bf16_f32 v72, v72, v73
	v_cvt_pk_bf16_f32 v73, v74, v75
	global_store_dwordx2 v227, v[72:73], s[56:57] offset:1024
	v_pk_mul_f32 v[76:77], v[76:77], v[218:219] op_sel_hi:[1,0]
	v_pk_mul_f32 v[78:79], v[78:79], v[218:219] op_sel_hi:[1,0]
	v_pk_fma_f32 v[76:77], v[76:77], v[190:191], v[206:207]
	v_pk_fma_f32 v[78:79], v[78:79], v[192:193], v[208:209]
	v_cvt_pk_bf16_f32 v76, v76, v77
	v_cvt_pk_bf16_f32 v77, v78, v79
	global_store_dwordx2 v227, v[76:77], s[56:57] offset:1536
	s_add_u32 s56, s56, 0x4000
	s_addc_u32 s57, s57, 0
	v_pk_mul_f32 v[80:81], v[80:81], v[220:221] op_sel_hi:[1,0]
	v_pk_mul_f32 v[82:83], v[82:83], v[220:221] op_sel_hi:[1,0]
	v_pk_fma_f32 v[80:81], v[80:81], v[178:179], v[194:195]
	v_pk_fma_f32 v[82:83], v[82:83], v[180:181], v[196:197]
	v_cvt_pk_bf16_f32 v80, v80, v81
	v_cvt_pk_bf16_f32 v81, v82, v83
	global_store_dwordx2 v227, v[80:81], s[56:57]
	v_pk_mul_f32 v[84:85], v[84:85], v[220:221] op_sel_hi:[1,0]
	v_pk_mul_f32 v[86:87], v[86:87], v[220:221] op_sel_hi:[1,0]
	v_pk_fma_f32 v[84:85], v[84:85], v[182:183], v[198:199]
	v_pk_fma_f32 v[86:87], v[86:87], v[184:185], v[200:201]
	v_cvt_pk_bf16_f32 v84, v84, v85
	v_cvt_pk_bf16_f32 v85, v86, v87
	global_store_dwordx2 v227, v[84:85], s[56:57] offset:512
	v_pk_mul_f32 v[88:89], v[88:89], v[220:221] op_sel_hi:[1,0]
	v_pk_mul_f32 v[90:91], v[90:91], v[220:221] op_sel_hi:[1,0]
	v_pk_fma_f32 v[88:89], v[88:89], v[186:187], v[202:203]
	v_pk_fma_f32 v[90:91], v[90:91], v[188:189], v[204:205]
	v_cvt_pk_bf16_f32 v88, v88, v89
	v_cvt_pk_bf16_f32 v89, v90, v91
	global_store_dwordx2 v227, v[88:89], s[56:57] offset:1024
	v_pk_mul_f32 v[92:93], v[92:93], v[220:221] op_sel_hi:[1,0]
	v_pk_mul_f32 v[94:95], v[94:95], v[220:221] op_sel_hi:[1,0]
	v_pk_fma_f32 v[92:93], v[92:93], v[190:191], v[206:207]
	v_pk_fma_f32 v[94:95], v[94:95], v[192:193], v[208:209]
	v_cvt_pk_bf16_f32 v92, v92, v93
	v_cvt_pk_bf16_f32 v93, v94, v95
	global_store_dwordx2 v227, v[92:93], s[56:57] offset:1536
	s_add_u32 s56, s56, 0x4000
	s_addc_u32 s57, s57, 0
	v_pk_mul_f32 v[134:135], v[134:135], v[222:223] op_sel_hi:[1,0]
	v_pk_mul_f32 v[136:137], v[136:137], v[222:223] op_sel_hi:[1,0]
	v_pk_fma_f32 v[134:135], v[134:135], v[178:179], v[194:195]
	v_pk_fma_f32 v[136:137], v[136:137], v[180:181], v[196:197]
	v_cvt_pk_bf16_f32 v134, v134, v135
	v_cvt_pk_bf16_f32 v135, v136, v137
	global_store_dwordx2 v227, v[134:135], s[56:57]
	v_pk_mul_f32 v[138:139], v[138:139], v[222:223] op_sel_hi:[1,0]
	v_pk_mul_f32 v[140:141], v[140:141], v[222:223] op_sel_hi:[1,0]
	v_pk_fma_f32 v[138:139], v[138:139], v[182:183], v[198:199]
	v_pk_fma_f32 v[140:141], v[140:141], v[184:185], v[200:201]
	v_cvt_pk_bf16_f32 v138, v138, v139
	v_cvt_pk_bf16_f32 v139, v140, v141
	global_store_dwordx2 v227, v[138:139], s[56:57] offset:512
	v_pk_mul_f32 v[142:143], v[142:143], v[222:223] op_sel_hi:[1,0]
	v_pk_mul_f32 v[144:145], v[144:145], v[222:223] op_sel_hi:[1,0]
	v_pk_fma_f32 v[142:143], v[142:143], v[186:187], v[202:203]
	v_pk_fma_f32 v[144:145], v[144:145], v[188:189], v[204:205]
	v_cvt_pk_bf16_f32 v142, v142, v143
	v_cvt_pk_bf16_f32 v143, v144, v145
	global_store_dwordx2 v227, v[142:143], s[56:57] offset:1024
	v_pk_mul_f32 v[146:147], v[146:147], v[222:223] op_sel_hi:[1,0]
	v_pk_mul_f32 v[148:149], v[148:149], v[222:223] op_sel_hi:[1,0]
	v_pk_fma_f32 v[146:147], v[146:147], v[190:191], v[206:207]
	v_pk_fma_f32 v[148:149], v[148:149], v[192:193], v[208:209]
	v_cvt_pk_bf16_f32 v146, v146, v147
	v_cvt_pk_bf16_f32 v147, v148, v149
	global_store_dwordx2 v227, v[146:147], s[56:57] offset:1536
	s_add_u32 s56, s56, 0x4000
	s_addc_u32 s57, s57, 0
	v_pk_mul_f32 v[150:151], v[150:151], v[224:225] op_sel_hi:[1,0]
	v_pk_mul_f32 v[152:153], v[152:153], v[224:225] op_sel_hi:[1,0]
	v_pk_fma_f32 v[150:151], v[150:151], v[178:179], v[194:195]
	v_pk_fma_f32 v[152:153], v[152:153], v[180:181], v[196:197]
	v_cvt_pk_bf16_f32 v150, v150, v151
	v_cvt_pk_bf16_f32 v151, v152, v153
	global_store_dwordx2 v227, v[150:151], s[56:57]
	v_pk_mul_f32 v[154:155], v[154:155], v[224:225] op_sel_hi:[1,0]
	v_pk_mul_f32 v[156:157], v[156:157], v[224:225] op_sel_hi:[1,0]
	v_pk_fma_f32 v[154:155], v[154:155], v[182:183], v[198:199]
	v_pk_fma_f32 v[156:157], v[156:157], v[184:185], v[200:201]
	v_cvt_pk_bf16_f32 v154, v154, v155
	v_cvt_pk_bf16_f32 v155, v156, v157
	global_store_dwordx2 v227, v[154:155], s[56:57] offset:512
	v_pk_mul_f32 v[158:159], v[158:159], v[224:225] op_sel_hi:[1,0]
	v_pk_mul_f32 v[160:161], v[160:161], v[224:225] op_sel_hi:[1,0]
	v_pk_fma_f32 v[158:159], v[158:159], v[186:187], v[202:203]
	v_pk_fma_f32 v[160:161], v[160:161], v[188:189], v[204:205]
	v_cvt_pk_bf16_f32 v158, v158, v159
	v_cvt_pk_bf16_f32 v159, v160, v161
	global_store_dwordx2 v227, v[158:159], s[56:57] offset:1024
	v_pk_mul_f32 v[162:163], v[162:163], v[224:225] op_sel_hi:[1,0]
	v_pk_mul_f32 v[164:165], v[164:165], v[224:225] op_sel_hi:[1,0]
	v_pk_fma_f32 v[162:163], v[162:163], v[190:191], v[206:207]
	v_pk_fma_f32 v[164:165], v[164:165], v[192:193], v[208:209]
	v_cvt_pk_bf16_f32 v162, v162, v163
	v_cvt_pk_bf16_f32 v163, v164, v165
	global_store_dwordx2 v227, v[162:163], s[56:57] offset:1536

.LBB0_2067:
	s_or_b64 exec, exec, s[6:7]
	s_sext_i32_i8 s3, s20
	s_lshl_b32 s2, s2, 8
	s_lshl_b32 s3, s3, 6
	s_add_i32 s20, s2, s3
	s_add_u32 s18, s16, 0x56bc000
	s_addc_u32 s19, s17, 0
	s_sub_i32 s6, s21, s23
	s_lshl_b32 s7, s22, 5
	s_sub_i32 s6, s6, s7
	s_sext_i32_i8 s6, s6
	s_lshl_b32 s6, s6, 8
	v_mov_b32_e32 v1, v170
	s_lshl_b32 s2, s22, 11
	s_add_i32 s3, s3, s6
	s_waitcnt lgkmcnt(0)
	s_barrier
	s_load_dwordx2 s[52:53], s[0:1], 0xe8
	s_load_dwordx4 s[68:71], s[0:1], 0xd8
	s_mov_b32 s66, s20
	v_readfirstlane_b32 s65, v170
	v_and_b32_e32 v226, 63, v170
	v_mov_b32_e32 v228, 0x358637bd
	v_lshlrev_b32_e32 v227, 3, v226
	v_lshlrev_b32_e32 v226, 4, v226
	s_lshr_b32 s65, s65, 6
	s_add_i32 s66, s66, s65
	s_waitcnt lgkmcnt(0)
	global_load_dwordx4 v[178:181], v226, s[68:69]
	global_load_dwordx4 v[182:185], v226, s[68:69] offset:1024
	global_load_dwordx4 v[186:189], v226, s[68:69] offset:2048
	global_load_dwordx4 v[190:193], v226, s[68:69] offset:3072
	s_lshl_b32 s67, s66, 12
	s_add_u32 s56, s70, s67
	s_addc_u32 s57, s71, 0
	s_lshl_b32 s67, s66, 12
	s_add_u32 s54, s52, 0x46bc000
	s_addc_u32 s55, s53, 0
	s_add_u32 s54, s54, s67
	s_addc_u32 s55, s55, 0
	global_load_dwordx4 v[0:3], v226, s[54:55]
	global_load_dwordx4 v[4:7], v226, s[54:55] offset:1024
	global_load_dwordx4 v[8:11], v226, s[54:55] offset:2048
	global_load_dwordx4 v[12:15], v226, s[54:55] offset:3072
	s_add_u32 s54, s54, 0x8000
	s_addc_u32 s55, s55, 0
	global_load_dwordx4 v[16:19], v226, s[54:55]
	global_load_dwordx4 v[20:23], v226, s[54:55] offset:1024
	global_load_dwordx4 v[24:27], v226, s[54:55] offset:2048
	global_load_dwordx4 v[28:31], v226, s[54:55] offset:3072
	s_add_u32 s54, s54, 0x8000
	s_addc_u32 s55, s55, 0
	global_load_dwordx4 v[32:35], v226, s[54:55]
	global_load_dwordx4 v[36:39], v226, s[54:55] offset:1024
	global_load_dwordx4 v[40:43], v226, s[54:55] offset:2048
	global_load_dwordx4 v[44:47], v226, s[54:55] offset:3072
	s_add_u32 s54, s54, 0x8000
	s_addc_u32 s55, s55, 0
	global_load_dwordx4 v[48:51], v226, s[54:55]
	global_load_dwordx4 v[52:55], v226, s[54:55] offset:1024
	global_load_dwordx4 v[56:59], v226, s[54:55] offset:2048
	global_load_dwordx4 v[60:63], v226, s[54:55] offset:3072
	s_add_u32 s54, s54, 0x8000
	s_addc_u32 s55, s55, 0
	global_load_dwordx4 v[64:67], v226, s[54:55]
	global_load_dwordx4 v[68:71], v226, s[54:55] offset:1024
	global_load_dwordx4 v[72:75], v226, s[54:55] offset:2048
	global_load_dwordx4 v[76:79], v226, s[54:55] offset:3072
	s_add_u32 s54, s54, 0x8000
	s_addc_u32 s55, s55, 0
	global_load_dwordx4 v[80:83], v226, s[54:55]
	global_load_dwordx4 v[84:87], v226, s[54:55] offset:1024
	global_load_dwordx4 v[88:91], v226, s[54:55] offset:2048
	global_load_dwordx4 v[92:95], v226, s[54:55] offset:3072
	s_add_u32 s54, s54, 0x8000
	s_addc_u32 s55, s55, 0
	global_load_dwordx4 v[134:137], v226, s[54:55]
	global_load_dwordx4 v[138:141], v226, s[54:55] offset:1024
	global_load_dwordx4 v[142:145], v226, s[54:55] offset:2048
	global_load_dwordx4 v[146:149], v226, s[54:55] offset:3072
	s_add_u32 s54, s54, 0x8000
	s_addc_u32 s55, s55, 0
	global_load_dwordx4 v[150:153], v226, s[54:55]
	global_load_dwordx4 v[154:157], v226, s[54:55] offset:1024
	global_load_dwordx4 v[158:161], v226, s[54:55] offset:2048
	global_load_dwordx4 v[162:165], v226, s[54:55] offset:3072
	s_waitcnt vmcnt(28)
	v_mul_f32_e32 v210, v0, v0
	v_fmac_f32_e32 v210, v1, v1
	v_fmac_f32_e32 v210, v2, v2
	v_fmac_f32_e32 v210, v3, v3
	v_fmac_f32_e32 v210, v4, v4
	v_fmac_f32_e32 v210, v5, v5
	v_fmac_f32_e32 v210, v6, v6
	v_fmac_f32_e32 v210, v7, v7
	v_fmac_f32_e32 v210, v8, v8
	v_fmac_f32_e32 v210, v9, v9
	v_fmac_f32_e32 v210, v10, v10
	v_fmac_f32_e32 v210, v11, v11
	v_fmac_f32_e32 v210, v12, v12
	v_fmac_f32_e32 v210, v13, v13
	v_fmac_f32_e32 v210, v14, v14
	v_fmac_f32_e32 v210, v15, v15
	s_waitcnt vmcnt(24)
	v_mul_f32_e32 v212, v16, v16
	v_fmac_f32_e32 v212, v17, v17
	v_fmac_f32_e32 v212, v18, v18
	v_fmac_f32_e32 v212, v19, v19
	v_fmac_f32_e32 v212, v20, v20
	v_fmac_f32_e32 v212, v21, v21
	v_fmac_f32_e32 v212, v22, v22
	v_fmac_f32_e32 v212, v23, v23
	v_fmac_f32_e32 v212, v24, v24
	v_fmac_f32_e32 v212, v25, v25
	v_fmac_f32_e32 v212, v26, v26
	v_fmac_f32_e32 v212, v27, v27
	v_fmac_f32_e32 v212, v28, v28
	v_fmac_f32_e32 v212, v29, v29
	v_fmac_f32_e32 v212, v30, v30
	v_fmac_f32_e32 v212, v31, v31
	s_waitcnt vmcnt(20)
	v_mul_f32_e32 v214, v32, v32
	v_fmac_f32_e32 v214, v33, v33
	v_fmac_f32_e32 v214, v34, v34
	v_fmac_f32_e32 v214, v35, v35
	v_fmac_f32_e32 v214, v36, v36
	v_fmac_f32_e32 v214, v37, v37
	v_fmac_f32_e32 v214, v38, v38
	v_fmac_f32_e32 v214, v39, v39
	v_fmac_f32_e32 v214, v40, v40
	v_fmac_f32_e32 v214, v41, v41
	v_fmac_f32_e32 v214, v42, v42
	v_fmac_f32_e32 v214, v43, v43
	v_fmac_f32_e32 v214, v44, v44
	v_fmac_f32_e32 v214, v45, v45
	v_fmac_f32_e32 v214, v46, v46
	v_fmac_f32_e32 v214, v47, v47
	s_waitcnt vmcnt(16)
	v_mul_f32_e32 v216, v48, v48
	v_fmac_f32_e32 v216, v49, v49
	v_fmac_f32_e32 v216, v50, v50
	v_fmac_f32_e32 v216, v51, v51
	v_fmac_f32_e32 v216, v52, v52
	v_fmac_f32_e32 v216, v53, v53
	v_fmac_f32_e32 v216, v54, v54
	v_fmac_f32_e32 v216, v55, v55
	v_fmac_f32_e32 v216, v56, v56
	v_fmac_f32_e32 v216, v57, v57
	v_fmac_f32_e32 v216, v58, v58
	v_fmac_f32_e32 v216, v59, v59
	v_fmac_f32_e32 v216, v60, v60
	v_fmac_f32_e32 v216, v61, v61
	v_fmac_f32_e32 v216, v62, v62
	v_fmac_f32_e32 v216, v63, v63
	s_waitcnt vmcnt(12)
	v_mul_f32_e32 v218, v64, v64
	v_fmac_f32_e32 v218, v65, v65
	v_fmac_f32_e32 v218, v66, v66
	v_fmac_f32_e32 v218, v67, v67
	v_fmac_f32_e32 v218, v68, v68
	v_fmac_f32_e32 v218, v69, v69
	v_fmac_f32_e32 v218, v70, v70
	v_fmac_f32_e32 v218, v71, v71
	v_fmac_f32_e32 v218, v72, v72
	v_fmac_f32_e32 v218, v73, v73
	v_fmac_f32_e32 v218, v74, v74
	v_fmac_f32_e32 v218, v75, v75
	v_fmac_f32_e32 v218, v76, v76
	v_fmac_f32_e32 v218, v77, v77
	v_fmac_f32_e32 v218, v78, v78
	v_fmac_f32_e32 v218, v79, v79
	s_waitcnt vmcnt(8)
	v_mul_f32_e32 v220, v80, v80
	v_fmac_f32_e32 v220, v81, v81
	v_fmac_f32_e32 v220, v82, v82
	v_fmac_f32_e32 v220, v83, v83
	v_fmac_f32_e32 v220, v84, v84
	v_fmac_f32_e32 v220, v85, v85
	v_fmac_f32_e32 v220, v86, v86
	v_fmac_f32_e32 v220, v87, v87
	v_fmac_f32_e32 v220, v88, v88
	v_fmac_f32_e32 v220, v89, v89
	v_fmac_f32_e32 v220, v90, v90
	v_fmac_f32_e32 v220, v91, v91
	v_fmac_f32_e32 v220, v92, v92
	v_fmac_f32_e32 v220, v93, v93
	v_fmac_f32_e32 v220, v94, v94
	v_fmac_f32_e32 v220, v95, v95
	s_waitcnt vmcnt(4)
	v_mul_f32_e32 v222, v134, v134
	v_fmac_f32_e32 v222, v135, v135
	v_fmac_f32_e32 v222, v136, v136
	v_fmac_f32_e32 v222, v137, v137
	v_fmac_f32_e32 v222, v138, v138
	v_fmac_f32_e32 v222, v139, v139
	v_fmac_f32_e32 v222, v140, v140
	v_fmac_f32_e32 v222, v141, v141
	v_fmac_f32_e32 v222, v142, v142
	v_fmac_f32_e32 v222, v143, v143
	v_fmac_f32_e32 v222, v144, v144
	v_fmac_f32_e32 v222, v145, v145
	v_fmac_f32_e32 v222, v146, v146
	v_fmac_f32_e32 v222, v147, v147
	v_fmac_f32_e32 v222, v148, v148
	v_fmac_f32_e32 v222, v149, v149
	s_waitcnt vmcnt(0)
	v_mul_f32_e32 v224, v150, v150
	v_fmac_f32_e32 v224, v151, v151
	v_fmac_f32_e32 v224, v152, v152
	v_fmac_f32_e32 v224, v153, v153
	v_fmac_f32_e32 v224, v154, v154
	v_fmac_f32_e32 v224, v155, v155
	v_fmac_f32_e32 v224, v156, v156
	v_fmac_f32_e32 v224, v157, v157
	v_fmac_f32_e32 v224, v158, v158
	v_fmac_f32_e32 v224, v159, v159
	v_fmac_f32_e32 v224, v160, v160
	v_fmac_f32_e32 v224, v161, v161
	v_fmac_f32_e32 v224, v162, v162
	v_fmac_f32_e32 v224, v163, v163
	v_fmac_f32_e32 v224, v164, v164
	v_fmac_f32_e32 v224, v165, v165
	ds_bpermute_b32 v211, v171, v210
	ds_bpermute_b32 v213, v171, v212
	ds_bpermute_b32 v215, v171, v214
	ds_bpermute_b32 v217, v171, v216
	ds_bpermute_b32 v219, v171, v218
	ds_bpermute_b32 v221, v171, v220
	ds_bpermute_b32 v223, v171, v222
	ds_bpermute_b32 v225, v171, v224
	s_waitcnt lgkmcnt(7)
	v_add_f32_e32 v210, v210, v211
	s_waitcnt lgkmcnt(6)
	v_add_f32_e32 v212, v212, v213
	s_waitcnt lgkmcnt(5)
	v_add_f32_e32 v214, v214, v215
	s_waitcnt lgkmcnt(4)
	v_add_f32_e32 v216, v216, v217
	s_waitcnt lgkmcnt(3)
	v_add_f32_e32 v218, v218, v219
	s_waitcnt lgkmcnt(2)
	v_add_f32_e32 v220, v220, v221
	s_waitcnt lgkmcnt(1)
	v_add_f32_e32 v222, v222, v223
	s_waitcnt lgkmcnt(0)
	v_add_f32_e32 v224, v224, v225
	ds_bpermute_b32 v211, v172, v210
	ds_bpermute_b32 v213, v172, v212
	ds_bpermute_b32 v215, v172, v214
	ds_bpermute_b32 v217, v172, v216
	ds_bpermute_b32 v219, v172, v218
	ds_bpermute_b32 v221, v172, v220
	ds_bpermute_b32 v223, v172, v222
	ds_bpermute_b32 v225, v172, v224
	s_waitcnt lgkmcnt(7)
	v_add_f32_e32 v210, v210, v211
	s_waitcnt lgkmcnt(6)
	v_add_f32_e32 v212, v212, v213
	s_waitcnt lgkmcnt(5)
	v_add_f32_e32 v214, v214, v215
	s_waitcnt lgkmcnt(4)
	v_add_f32_e32 v216, v216, v217
	s_waitcnt lgkmcnt(3)
	v_add_f32_e32 v218, v218, v219
	s_waitcnt lgkmcnt(2)
	v_add_f32_e32 v220, v220, v221
	s_waitcnt lgkmcnt(1)
	v_add_f32_e32 v222, v222, v223
	s_waitcnt lgkmcnt(0)
	v_add_f32_e32 v224, v224, v225
	ds_bpermute_b32 v211, v173, v210
	ds_bpermute_b32 v213, v173, v212
	ds_bpermute_b32 v215, v173, v214
	ds_bpermute_b32 v217, v173, v216
	ds_bpermute_b32 v219, v173, v218
	ds_bpermute_b32 v221, v173, v220
	ds_bpermute_b32 v223, v173, v222
	ds_bpermute_b32 v225, v173, v224
	s_waitcnt lgkmcnt(7)
	v_add_f32_e32 v210, v210, v211
	s_waitcnt lgkmcnt(6)
	v_add_f32_e32 v212, v212, v213
	s_waitcnt lgkmcnt(5)
	v_add_f32_e32 v214, v214, v215
	s_waitcnt lgkmcnt(4)
	v_add_f32_e32 v216, v216, v217
	s_waitcnt lgkmcnt(3)
	v_add_f32_e32 v218, v218, v219
	s_waitcnt lgkmcnt(2)
	v_add_f32_e32 v220, v220, v221
	s_waitcnt lgkmcnt(1)
	v_add_f32_e32 v222, v222, v223
	s_waitcnt lgkmcnt(0)
	v_add_f32_e32 v224, v224, v225
	ds_bpermute_b32 v211, v174, v210
	ds_bpermute_b32 v213, v174, v212
	ds_bpermute_b32 v215, v174, v214
	ds_bpermute_b32 v217, v174, v216
	ds_bpermute_b32 v219, v174, v218
	ds_bpermute_b32 v221, v174, v220
	ds_bpermute_b32 v223, v174, v222
	ds_bpermute_b32 v225, v174, v224
	s_waitcnt lgkmcnt(7)
	v_add_f32_e32 v210, v210, v211
	s_waitcnt lgkmcnt(6)
	v_add_f32_e32 v212, v212, v213
	s_waitcnt lgkmcnt(5)
	v_add_f32_e32 v214, v214, v215
	s_waitcnt lgkmcnt(4)
	v_add_f32_e32 v216, v216, v217
	s_waitcnt lgkmcnt(3)
	v_add_f32_e32 v218, v218, v219
	s_waitcnt lgkmcnt(2)
	v_add_f32_e32 v220, v220, v221
	s_waitcnt lgkmcnt(1)
	v_add_f32_e32 v222, v222, v223
	s_waitcnt lgkmcnt(0)
	v_add_f32_e32 v224, v224, v225
	ds_bpermute_b32 v211, v175, v210
	ds_bpermute_b32 v213, v175, v212
	ds_bpermute_b32 v215, v175, v214
	ds_bpermute_b32 v217, v175, v216
	ds_bpermute_b32 v219, v175, v218
	ds_bpermute_b32 v221, v175, v220
	ds_bpermute_b32 v223, v175, v222
	ds_bpermute_b32 v225, v175, v224
	s_waitcnt lgkmcnt(7)
	v_add_f32_e32 v210, v210, v211
	s_waitcnt lgkmcnt(6)
	v_add_f32_e32 v212, v212, v213
	s_waitcnt lgkmcnt(5)
	v_add_f32_e32 v214, v214, v215
	s_waitcnt lgkmcnt(4)
	v_add_f32_e32 v216, v216, v217
	s_waitcnt lgkmcnt(3)
	v_add_f32_e32 v218, v218, v219
	s_waitcnt lgkmcnt(2)
	v_add_f32_e32 v220, v220, v221
	s_waitcnt lgkmcnt(1)
	v_add_f32_e32 v222, v222, v223
	s_waitcnt lgkmcnt(0)
	v_add_f32_e32 v224, v224, v225
	ds_bpermute_b32 v211, v176, v210
	ds_bpermute_b32 v213, v176, v212
	ds_bpermute_b32 v215, v176, v214
	ds_bpermute_b32 v217, v176, v216
	ds_bpermute_b32 v219, v176, v218
	ds_bpermute_b32 v221, v176, v220
	ds_bpermute_b32 v223, v176, v222
	ds_bpermute_b32 v225, v176, v224
	s_waitcnt lgkmcnt(7)
	v_add_f32_e32 v210, v210, v211
	s_waitcnt lgkmcnt(6)
	v_add_f32_e32 v212, v212, v213
	s_waitcnt lgkmcnt(5)
	v_add_f32_e32 v214, v214, v215
	s_waitcnt lgkmcnt(4)
	v_add_f32_e32 v216, v216, v217
	s_waitcnt lgkmcnt(3)
	v_add_f32_e32 v218, v218, v219
	s_waitcnt lgkmcnt(2)
	v_add_f32_e32 v220, v220, v221
	s_waitcnt lgkmcnt(1)
	v_add_f32_e32 v222, v222, v223
	s_waitcnt lgkmcnt(0)
	v_add_f32_e32 v224, v224, v225
	v_fmamk_f32 v210, v210, 0x3a800000, v228
	v_fmamk_f32 v212, v212, 0x3a800000, v228
	v_fmamk_f32 v214, v214, 0x3a800000, v228
	v_fmamk_f32 v216, v216, 0x3a800000, v228
	v_fmamk_f32 v218, v218, 0x3a800000, v228
	v_fmamk_f32 v220, v220, 0x3a800000, v228
	v_fmamk_f32 v222, v222, 0x3a800000, v228
	v_fmamk_f32 v224, v224, 0x3a800000, v228
	v_rsq_f32_e32 v210, v210
	v_rsq_f32_e32 v212, v212
	v_rsq_f32_e32 v214, v214
	v_rsq_f32_e32 v216, v216
	v_rsq_f32_e32 v218, v218
	v_rsq_f32_e32 v220, v220
	v_rsq_f32_e32 v222, v222
	v_rsq_f32_e32 v224, v224
	v_pk_mul_f32 v[0:1], v[0:1], v[210:211] op_sel_hi:[1,0]
	v_pk_mul_f32 v[2:3], v[2:3], v[210:211] op_sel_hi:[1,0]
	v_pk_mul_f32 v[0:1], v[0:1], v[178:179]
	v_pk_mul_f32 v[2:3], v[2:3], v[180:181]
	global_store_dwordx4 v226, v[0:3], s[56:57] nt
	v_pk_mul_f32 v[4:5], v[4:5], v[210:211] op_sel_hi:[1,0]
	v_pk_mul_f32 v[6:7], v[6:7], v[210:211] op_sel_hi:[1,0]
	v_pk_mul_f32 v[4:5], v[4:5], v[182:183]
	v_pk_mul_f32 v[6:7], v[6:7], v[184:185]
	global_store_dwordx4 v226, v[4:7], s[56:57] offset:1024 nt
	v_pk_mul_f32 v[8:9], v[8:9], v[210:211] op_sel_hi:[1,0]
	v_pk_mul_f32 v[10:11], v[10:11], v[210:211] op_sel_hi:[1,0]
	v_pk_mul_f32 v[8:9], v[8:9], v[186:187]
	v_pk_mul_f32 v[10:11], v[10:11], v[188:189]
	global_store_dwordx4 v226, v[8:11], s[56:57] offset:2048 nt
	v_pk_mul_f32 v[12:13], v[12:13], v[210:211] op_sel_hi:[1,0]
	v_pk_mul_f32 v[14:15], v[14:15], v[210:211] op_sel_hi:[1,0]
	v_pk_mul_f32 v[12:13], v[12:13], v[190:191]
	v_pk_mul_f32 v[14:15], v[14:15], v[192:193]
	global_store_dwordx4 v226, v[12:15], s[56:57] offset:3072 nt
	s_add_u32 s56, s56, 0x8000
	s_addc_u32 s57, s57, 0
	v_pk_mul_f32 v[16:17], v[16:17], v[212:213] op_sel_hi:[1,0]
	v_pk_mul_f32 v[18:19], v[18:19], v[212:213] op_sel_hi:[1,0]
	v_pk_mul_f32 v[16:17], v[16:17], v[178:179]
	v_pk_mul_f32 v[18:19], v[18:19], v[180:181]
	global_store_dwordx4 v226, v[16:19], s[56:57] nt
	v_pk_mul_f32 v[20:21], v[20:21], v[212:213] op_sel_hi:[1,0]
	v_pk_mul_f32 v[22:23], v[22:23], v[212:213] op_sel_hi:[1,0]
	v_pk_mul_f32 v[20:21], v[20:21], v[182:183]
	v_pk_mul_f32 v[22:23], v[22:23], v[184:185]
	global_store_dwordx4 v226, v[20:23], s[56:57] offset:1024 nt
	v_pk_mul_f32 v[24:25], v[24:25], v[212:213] op_sel_hi:[1,0]
	v_pk_mul_f32 v[26:27], v[26:27], v[212:213] op_sel_hi:[1,0]
	v_pk_mul_f32 v[24:25], v[24:25], v[186:187]
	v_pk_mul_f32 v[26:27], v[26:27], v[188:189]
	global_store_dwordx4 v226, v[24:27], s[56:57] offset:2048 nt
	v_pk_mul_f32 v[28:29], v[28:29], v[212:213] op_sel_hi:[1,0]
	v_pk_mul_f32 v[30:31], v[30:31], v[212:213] op_sel_hi:[1,0]
	v_pk_mul_f32 v[28:29], v[28:29], v[190:191]
	v_pk_mul_f32 v[30:31], v[30:31], v[192:193]
	global_store_dwordx4 v226, v[28:31], s[56:57] offset:3072 nt
	s_add_u32 s56, s56, 0x8000
	s_addc_u32 s57, s57, 0
	v_pk_mul_f32 v[32:33], v[32:33], v[214:215] op_sel_hi:[1,0]
	v_pk_mul_f32 v[34:35], v[34:35], v[214:215] op_sel_hi:[1,0]
	v_pk_mul_f32 v[32:33], v[32:33], v[178:179]
	v_pk_mul_f32 v[34:35], v[34:35], v[180:181]
	global_store_dwordx4 v226, v[32:35], s[56:57] nt
	v_pk_mul_f32 v[36:37], v[36:37], v[214:215] op_sel_hi:[1,0]
	v_pk_mul_f32 v[38:39], v[38:39], v[214:215] op_sel_hi:[1,0]
	v_pk_mul_f32 v[36:37], v[36:37], v[182:183]
	v_pk_mul_f32 v[38:39], v[38:39], v[184:185]
	global_store_dwordx4 v226, v[36:39], s[56:57] offset:1024 nt
	v_pk_mul_f32 v[40:41], v[40:41], v[214:215] op_sel_hi:[1,0]
	v_pk_mul_f32 v[42:43], v[42:43], v[214:215] op_sel_hi:[1,0]
	v_pk_mul_f32 v[40:41], v[40:41], v[186:187]
	v_pk_mul_f32 v[42:43], v[42:43], v[188:189]
	global_store_dwordx4 v226, v[40:43], s[56:57] offset:2048 nt
	v_pk_mul_f32 v[44:45], v[44:45], v[214:215] op_sel_hi:[1,0]
	v_pk_mul_f32 v[46:47], v[46:47], v[214:215] op_sel_hi:[1,0]
	v_pk_mul_f32 v[44:45], v[44:45], v[190:191]
	v_pk_mul_f32 v[46:47], v[46:47], v[192:193]
	global_store_dwordx4 v226, v[44:47], s[56:57] offset:3072 nt
	s_add_u32 s56, s56, 0x8000
	s_addc_u32 s57, s57, 0
	v_pk_mul_f32 v[48:49], v[48:49], v[216:217] op_sel_hi:[1,0]
	v_pk_mul_f32 v[50:51], v[50:51], v[216:217] op_sel_hi:[1,0]
	v_pk_mul_f32 v[48:49], v[48:49], v[178:179]
	v_pk_mul_f32 v[50:51], v[50:51], v[180:181]
	global_store_dwordx4 v226, v[48:51], s[56:57] nt
	v_pk_mul_f32 v[52:53], v[52:53], v[216:217] op_sel_hi:[1,0]
	v_pk_mul_f32 v[54:55], v[54:55], v[216:217] op_sel_hi:[1,0]
	v_pk_mul_f32 v[52:53], v[52:53], v[182:183]
	v_pk_mul_f32 v[54:55], v[54:55], v[184:185]
	global_store_dwordx4 v226, v[52:55], s[56:57] offset:1024 nt
	v_pk_mul_f32 v[56:57], v[56:57], v[216:217] op_sel_hi:[1,0]
	v_pk_mul_f32 v[58:59], v[58:59], v[216:217] op_sel_hi:[1,0]
	v_pk_mul_f32 v[56:57], v[56:57], v[186:187]
	v_pk_mul_f32 v[58:59], v[58:59], v[188:189]
	global_store_dwordx4 v226, v[56:59], s[56:57] offset:2048 nt
	v_pk_mul_f32 v[60:61], v[60:61], v[216:217] op_sel_hi:[1,0]
	v_pk_mul_f32 v[62:63], v[62:63], v[216:217] op_sel_hi:[1,0]
	v_pk_mul_f32 v[60:61], v[60:61], v[190:191]
	v_pk_mul_f32 v[62:63], v[62:63], v[192:193]
	global_store_dwordx4 v226, v[60:63], s[56:57] offset:3072 nt
	s_add_u32 s56, s56, 0x8000
	s_addc_u32 s57, s57, 0
	v_pk_mul_f32 v[64:65], v[64:65], v[218:219] op_sel_hi:[1,0]
	v_pk_mul_f32 v[66:67], v[66:67], v[218:219] op_sel_hi:[1,0]
	v_pk_mul_f32 v[64:65], v[64:65], v[178:179]
	v_pk_mul_f32 v[66:67], v[66:67], v[180:181]
	global_store_dwordx4 v226, v[64:67], s[56:57] nt
	v_pk_mul_f32 v[68:69], v[68:69], v[218:219] op_sel_hi:[1,0]
	v_pk_mul_f32 v[70:71], v[70:71], v[218:219] op_sel_hi:[1,0]
	v_pk_mul_f32 v[68:69], v[68:69], v[182:183]
	v_pk_mul_f32 v[70:71], v[70:71], v[184:185]
	global_store_dwordx4 v226, v[68:71], s[56:57] offset:1024 nt
	v_pk_mul_f32 v[72:73], v[72:73], v[218:219] op_sel_hi:[1,0]
	v_pk_mul_f32 v[74:75], v[74:75], v[218:219] op_sel_hi:[1,0]
	v_pk_mul_f32 v[72:73], v[72:73], v[186:187]
	v_pk_mul_f32 v[74:75], v[74:75], v[188:189]
	global_store_dwordx4 v226, v[72:75], s[56:57] offset:2048 nt
	v_pk_mul_f32 v[76:77], v[76:77], v[218:219] op_sel_hi:[1,0]
	v_pk_mul_f32 v[78:79], v[78:79], v[218:219] op_sel_hi:[1,0]
	v_pk_mul_f32 v[76:77], v[76:77], v[190:191]
	v_pk_mul_f32 v[78:79], v[78:79], v[192:193]
	global_store_dwordx4 v226, v[76:79], s[56:57] offset:3072 nt
	s_add_u32 s56, s56, 0x8000
	s_addc_u32 s57, s57, 0
	v_pk_mul_f32 v[80:81], v[80:81], v[220:221] op_sel_hi:[1,0]
	v_pk_mul_f32 v[82:83], v[82:83], v[220:221] op_sel_hi:[1,0]
	v_pk_mul_f32 v[80:81], v[80:81], v[178:179]
	v_pk_mul_f32 v[82:83], v[82:83], v[180:181]
	global_store_dwordx4 v226, v[80:83], s[56:57] nt
	v_pk_mul_f32 v[84:85], v[84:85], v[220:221] op_sel_hi:[1,0]
	v_pk_mul_f32 v[86:87], v[86:87], v[220:221] op_sel_hi:[1,0]
	v_pk_mul_f32 v[84:85], v[84:85], v[182:183]
	v_pk_mul_f32 v[86:87], v[86:87], v[184:185]
	global_store_dwordx4 v226, v[84:87], s[56:57] offset:1024 nt
	v_pk_mul_f32 v[88:89], v[88:89], v[220:221] op_sel_hi:[1,0]
	v_pk_mul_f32 v[90:91], v[90:91], v[220:221] op_sel_hi:[1,0]
	v_pk_mul_f32 v[88:89], v[88:89], v[186:187]
	v_pk_mul_f32 v[90:91], v[90:91], v[188:189]
	global_store_dwordx4 v226, v[88:91], s[56:57] offset:2048 nt
	v_pk_mul_f32 v[92:93], v[92:93], v[220:221] op_sel_hi:[1,0]
	v_pk_mul_f32 v[94:95], v[94:95], v[220:221] op_sel_hi:[1,0]
	v_pk_mul_f32 v[92:93], v[92:93], v[190:191]
	v_pk_mul_f32 v[94:95], v[94:95], v[192:193]
	global_store_dwordx4 v226, v[92:95], s[56:57] offset:3072 nt
	s_add_u32 s56, s56, 0x8000
	s_addc_u32 s57, s57, 0
	v_pk_mul_f32 v[134:135], v[134:135], v[222:223] op_sel_hi:[1,0]
	v_pk_mul_f32 v[136:137], v[136:137], v[222:223] op_sel_hi:[1,0]
	v_pk_mul_f32 v[134:135], v[134:135], v[178:179]
	v_pk_mul_f32 v[136:137], v[136:137], v[180:181]
	global_store_dwordx4 v226, v[134:137], s[56:57] nt
	v_pk_mul_f32 v[138:139], v[138:139], v[222:223] op_sel_hi:[1,0]
	v_pk_mul_f32 v[140:141], v[140:141], v[222:223] op_sel_hi:[1,0]
	v_pk_mul_f32 v[138:139], v[138:139], v[182:183]
	v_pk_mul_f32 v[140:141], v[140:141], v[184:185]
	global_store_dwordx4 v226, v[138:141], s[56:57] offset:1024 nt
	v_pk_mul_f32 v[142:143], v[142:143], v[222:223] op_sel_hi:[1,0]
	v_pk_mul_f32 v[144:145], v[144:145], v[222:223] op_sel_hi:[1,0]
	v_pk_mul_f32 v[142:143], v[142:143], v[186:187]
	v_pk_mul_f32 v[144:145], v[144:145], v[188:189]
	global_store_dwordx4 v226, v[142:145], s[56:57] offset:2048 nt
	v_pk_mul_f32 v[146:147], v[146:147], v[222:223] op_sel_hi:[1,0]
	v_pk_mul_f32 v[148:149], v[148:149], v[222:223] op_sel_hi:[1,0]
	v_pk_mul_f32 v[146:147], v[146:147], v[190:191]
	v_pk_mul_f32 v[148:149], v[148:149], v[192:193]
	global_store_dwordx4 v226, v[146:149], s[56:57] offset:3072 nt
	s_add_u32 s56, s56, 0x8000
	s_addc_u32 s57, s57, 0
	v_pk_mul_f32 v[150:151], v[150:151], v[224:225] op_sel_hi:[1,0]
	v_pk_mul_f32 v[152:153], v[152:153], v[224:225] op_sel_hi:[1,0]
	v_pk_mul_f32 v[150:151], v[150:151], v[178:179]
	v_pk_mul_f32 v[152:153], v[152:153], v[180:181]
	global_store_dwordx4 v226, v[150:153], s[56:57] nt
	v_pk_mul_f32 v[154:155], v[154:155], v[224:225] op_sel_hi:[1,0]
	v_pk_mul_f32 v[156:157], v[156:157], v[224:225] op_sel_hi:[1,0]
	v_pk_mul_f32 v[154:155], v[154:155], v[182:183]
	v_pk_mul_f32 v[156:157], v[156:157], v[184:185]
	global_store_dwordx4 v226, v[154:157], s[56:57] offset:1024 nt
	v_pk_mul_f32 v[158:159], v[158:159], v[224:225] op_sel_hi:[1,0]
	v_pk_mul_f32 v[160:161], v[160:161], v[224:225] op_sel_hi:[1,0]
	v_pk_mul_f32 v[158:159], v[158:159], v[186:187]
	v_pk_mul_f32 v[160:161], v[160:161], v[188:189]
	global_store_dwordx4 v226, v[158:161], s[56:57] offset:2048 nt
	v_pk_mul_f32 v[162:163], v[162:163], v[224:225] op_sel_hi:[1,0]
	v_pk_mul_f32 v[164:165], v[164:165], v[224:225] op_sel_hi:[1,0]
	v_pk_mul_f32 v[162:163], v[162:163], v[190:191]
	v_pk_mul_f32 v[164:165], v[164:165], v[192:193]
	global_store_dwordx4 v226, v[162:165], s[56:57] offset:3072 nt
